# K-loop MFMA order n-major: per B-fragment pair, the 4 A-fragment pairs, k0 then k1 back to back per accumulator (32-MFMA segment)
# speedup vs baseline: 1.0117x; 1.0029x over previous
.LBB0_411:
	s_add_u32 s16, s14, 0xfffc0080
	s_addc_u32 s17, s15, -1
	s_add_i32 s51, 0, 0x10000
	s_cmp_eq_u32 s50, 12
	s_cselect_b32 s21, s9, s17
	s_cselect_b32 s20, s46, s16
	s_cselect_b32 s17, s5, s49
	s_cselect_b32 s16, s47, s48
	s_add_i32 s54, 0, 0x14000
	v_add_u32_e32 v154, s51, v181
	v_add_u32_e32 v162, s54, v181
	ds_read_b128 v[130:133], v154
	ds_read_b128 v[134:137], v154 offset:1024
	ds_read_b128 v[150:153], v154 offset:2048
	ds_read_b128 v[154:157], v154 offset:3072
	ds_read_b128 v[158:161], v162
	ds_read_b128 v[174:177], v162 offset:1024
	ds_read_b128 v[186:189], v162 offset:2048
	ds_read_b128 v[190:193], v162 offset:3072
	s_add_i32 m0, s26, 0xc000
	ds_read_b128 v[194:197], v184
	ds_read_b128 v[198:201], v184 offset:1024
	ds_read_b128 v[202:205], v184 offset:2048
	ds_read_b128 v[206:209], v184 offset:3072
	ds_read_b128 v[224:227], v184 offset:4096
	ds_read_b128 v[228:231], v184 offset:5120
	ds_read_b128 v[232:235], v184 offset:6144
	ds_read_b128 v[236:239], v184 offset:7168
	global_load_lds_dwordx4 v146, s[14:15]
	s_add_i32 m0, s26, 0xe000
	s_nop 0
	global_load_lds_dwordx4 v148, s[14:15]
	s_waitcnt vmcnt(8)
	s_waitcnt lgkmcnt(0)
	s_barrier
	s_setprio 1
	s_waitcnt lgkmcnt(0)
	v_mfma_i32_16x16x64_i8 v[126:129], v[130:133], v[194:197], v[126:129]
	v_mfma_i32_16x16x64_i8 v[126:129], v[134:137], v[198:201], v[126:129]
	v_mfma_i32_16x16x64_i8 v[110:113], v[130:133], v[202:205], v[110:113]
	v_mfma_i32_16x16x64_i8 v[110:113], v[134:137], v[206:209], v[110:113]
	v_mfma_i32_16x16x64_i8 v[94:97], v[130:133], v[224:227], v[94:97]
	v_mfma_i32_16x16x64_i8 v[94:97], v[134:137], v[228:231], v[94:97]
	v_mfma_i32_16x16x64_i8 v[78:81], v[130:133], v[232:235], v[78:81]
	v_mfma_i32_16x16x64_i8 v[78:81], v[134:137], v[236:239], v[78:81]
	v_mfma_i32_16x16x64_i8 v[122:125], v[150:153], v[194:197], v[122:125]
	v_mfma_i32_16x16x64_i8 v[122:125], v[154:157], v[198:201], v[122:125]
	v_mfma_i32_16x16x64_i8 v[102:105], v[150:153], v[202:205], v[102:105]
	v_mfma_i32_16x16x64_i8 v[102:105], v[154:157], v[206:209], v[102:105]
	v_mfma_i32_16x16x64_i8 v[86:89], v[150:153], v[224:227], v[86:89]
	v_mfma_i32_16x16x64_i8 v[86:89], v[154:157], v[228:231], v[86:89]
	v_mfma_i32_16x16x64_i8 v[70:73], v[150:153], v[232:235], v[70:73]
	v_mfma_i32_16x16x64_i8 v[70:73], v[154:157], v[236:239], v[70:73]
	v_mfma_i32_16x16x64_i8 v[118:121], v[158:161], v[194:197], v[118:121]
	v_mfma_i32_16x16x64_i8 v[118:121], v[174:177], v[198:201], v[118:121]
	v_mfma_i32_16x16x64_i8 v[106:109], v[158:161], v[202:205], v[106:109]
	v_mfma_i32_16x16x64_i8 v[106:109], v[174:177], v[206:209], v[106:109]
	v_mfma_i32_16x16x64_i8 v[90:93], v[158:161], v[224:227], v[90:93]
	v_mfma_i32_16x16x64_i8 v[90:93], v[174:177], v[228:231], v[90:93]
	v_mfma_i32_16x16x64_i8 v[74:77], v[158:161], v[232:235], v[74:77]
	v_mfma_i32_16x16x64_i8 v[74:77], v[174:177], v[236:239], v[74:77]
	v_mfma_i32_16x16x64_i8 v[114:117], v[186:189], v[194:197], v[114:117]
	v_mfma_i32_16x16x64_i8 v[114:117], v[190:193], v[198:201], v[114:117]
	v_mfma_i32_16x16x64_i8 v[98:101], v[186:189], v[202:205], v[98:101]
	v_mfma_i32_16x16x64_i8 v[98:101], v[190:193], v[206:209], v[98:101]
	v_mfma_i32_16x16x64_i8 v[82:85], v[186:189], v[224:227], v[82:85]
	v_mfma_i32_16x16x64_i8 v[82:85], v[190:193], v[228:231], v[82:85]
	v_mfma_i32_16x16x64_i8 v[66:69], v[186:189], v[232:235], v[66:69]
	v_mfma_i32_16x16x64_i8 v[66:69], v[190:193], v[236:239], v[66:69]
	s_setprio 0
	s_barrier
	s_add_i32 s51, s51, s33
	v_lshl_add_u64 v[162:163], s[16:17], 0, v[0:1]
	s_mov_b32 m0, s51
	ds_read_b128 v[194:197], v184 offset:16384
	ds_read_b128 v[198:201], v184 offset:17408
	ds_read_b128 v[202:205], v184 offset:18432
	ds_read_b128 v[206:209], v184 offset:19456
	ds_read_b128 v[224:227], v184 offset:20480
	ds_read_b128 v[228:231], v184 offset:21504
	ds_read_b128 v[232:235], v184 offset:22528
	ds_read_b128 v[236:239], v184 offset:23552
	global_load_lds_dwordx4 v[162:163], off
	s_add_i32 m0, s51, 0x2000
	s_add_u32 s52, s16, 0x40000
	v_lshl_add_u64 v[164:165], s[16:17], 0, v[138:139]
	s_addc_u32 s53, s17, 0
	s_add_i32 s51, s54, s33
	global_load_lds_dwordx4 v[164:165], off
	s_mov_b32 m0, s51
	v_lshl_add_u64 v[168:169], s[20:21], 0, v[140:141]
	global_load_lds_dwordx4 v0, s[52:53]
	s_add_i32 m0, s51, 0x2000
	s_nop 0
	global_load_lds_dwordx4 v138, s[52:53]
	v_lshl_add_u64 v[166:167], s[20:21], 0, v[142:143]
	s_mov_b32 m0, s26
	s_nop 0
	global_load_lds_dwordx4 v[166:167], off
	s_mov_b32 m0, s27
	s_nop 0
	global_load_lds_dwordx4 v[168:169], off
	s_waitcnt vmcnt(8)
	s_waitcnt lgkmcnt(0)
	s_barrier
	s_setprio 1
	s_waitcnt lgkmcnt(0)
	v_mfma_i32_16x16x64_i8 v[62:65], v[130:133], v[194:197], v[62:65]
	v_mfma_i32_16x16x64_i8 v[62:65], v[134:137], v[198:201], v[62:65]
	v_mfma_i32_16x16x64_i8 v[46:49], v[130:133], v[202:205], v[46:49]
	v_mfma_i32_16x16x64_i8 v[46:49], v[134:137], v[206:209], v[46:49]
	v_mfma_i32_16x16x64_i8 v[30:33], v[130:133], v[224:227], v[30:33]
	v_mfma_i32_16x16x64_i8 v[30:33], v[134:137], v[228:231], v[30:33]
	v_mfma_i32_16x16x64_i8 v[14:17], v[130:133], v[232:235], v[14:17]
	v_mfma_i32_16x16x64_i8 v[14:17], v[134:137], v[236:239], v[14:17]
	v_mfma_i32_16x16x64_i8 v[54:57], v[150:153], v[194:197], v[54:57]
	v_mfma_i32_16x16x64_i8 v[54:57], v[154:157], v[198:201], v[54:57]
	v_mfma_i32_16x16x64_i8 v[38:41], v[150:153], v[202:205], v[38:41]
	v_mfma_i32_16x16x64_i8 v[38:41], v[154:157], v[206:209], v[38:41]
	v_mfma_i32_16x16x64_i8 v[22:25], v[150:153], v[224:227], v[22:25]
	v_mfma_i32_16x16x64_i8 v[22:25], v[154:157], v[228:231], v[22:25]
	v_mfma_i32_16x16x64_i8 v[6:9], v[150:153], v[232:235], v[6:9]
	v_mfma_i32_16x16x64_i8 v[6:9], v[154:157], v[236:239], v[6:9]
	v_mfma_i32_16x16x64_i8 v[58:61], v[158:161], v[194:197], v[58:61]
	v_mfma_i32_16x16x64_i8 v[58:61], v[174:177], v[198:201], v[58:61]
	v_mfma_i32_16x16x64_i8 v[42:45], v[158:161], v[202:205], v[42:45]
	v_mfma_i32_16x16x64_i8 v[42:45], v[174:177], v[206:209], v[42:45]
	v_mfma_i32_16x16x64_i8 v[26:29], v[158:161], v[224:227], v[26:29]
	v_mfma_i32_16x16x64_i8 v[26:29], v[174:177], v[228:231], v[26:29]
	v_mfma_i32_16x16x64_i8 v[10:13], v[158:161], v[232:235], v[10:13]
	v_mfma_i32_16x16x64_i8 v[10:13], v[174:177], v[236:239], v[10:13]
	v_mfma_i32_16x16x64_i8 v[50:53], v[186:189], v[194:197], v[50:53]
	v_mfma_i32_16x16x64_i8 v[50:53], v[190:193], v[198:201], v[50:53]
	v_mfma_i32_16x16x64_i8 v[34:37], v[186:189], v[202:205], v[34:37]
	v_mfma_i32_16x16x64_i8 v[34:37], v[190:193], v[206:209], v[34:37]
	v_mfma_i32_16x16x64_i8 v[18:21], v[186:189], v[224:227], v[18:21]
	v_mfma_i32_16x16x64_i8 v[18:21], v[190:193], v[228:231], v[18:21]
	v_mfma_i32_16x16x64_i8 v[2:5], v[186:189], v[232:235], v[2:5]
	v_mfma_i32_16x16x64_i8 v[2:5], v[190:193], v[236:239], v[2:5]
	s_setprio 0
	s_barrier
	s_add_i32 s51, 0, 0x18000
	s_add_i32 s52, 0, 0x1c000
	v_add_u32_e32 v154, s51, v181
	v_add_u32_e32 v170, s52, v181
	ds_read_b128 v[130:133], v154
	ds_read_b128 v[134:137], v154 offset:1024
	ds_read_b128 v[150:153], v154 offset:2048
	ds_read_b128 v[154:157], v154 offset:3072
	ds_read_b128 v[158:161], v170
	ds_read_b128 v[174:177], v170 offset:1024
	ds_read_b128 v[186:189], v170 offset:2048
	ds_read_b128 v[190:193], v170 offset:3072
	s_add_u32 s20, s20, 0x40000
	s_addc_u32 s21, s21, 0
	s_mov_b32 m0, s28
	ds_read_b128 v[194:197], v184 offset:32768
	ds_read_b128 v[198:201], v184 offset:33792
	ds_read_b128 v[202:205], v184 offset:34816
	ds_read_b128 v[206:209], v184 offset:35840
	ds_read_b128 v[224:227], v184 offset:36864
	ds_read_b128 v[228:231], v184 offset:37888
	ds_read_b128 v[232:235], v184 offset:38912
	ds_read_b128 v[236:239], v184 offset:39936
	global_load_lds_dwordx4 v142, s[20:21]
	s_mov_b32 m0, s29
	s_nop 0
	global_load_lds_dwordx4 v140, s[20:21]
	s_waitcnt vmcnt(8)
	s_waitcnt lgkmcnt(0)
	s_barrier
	s_setprio 1
	s_waitcnt lgkmcnt(0)
	v_mfma_i32_16x16x64_i8 v[126:129], v[130:133], v[194:197], v[126:129]
	v_mfma_i32_16x16x64_i8 v[126:129], v[134:137], v[198:201], v[126:129]
	v_mfma_i32_16x16x64_i8 v[110:113], v[130:133], v[202:205], v[110:113]
	v_mfma_i32_16x16x64_i8 v[110:113], v[134:137], v[206:209], v[110:113]
	v_mfma_i32_16x16x64_i8 v[94:97], v[130:133], v[224:227], v[94:97]
	v_mfma_i32_16x16x64_i8 v[94:97], v[134:137], v[228:231], v[94:97]
	v_mfma_i32_16x16x64_i8 v[78:81], v[130:133], v[232:235], v[78:81]
	v_mfma_i32_16x16x64_i8 v[78:81], v[134:137], v[236:239], v[78:81]
	v_mfma_i32_16x16x64_i8 v[122:125], v[150:153], v[194:197], v[122:125]
	v_mfma_i32_16x16x64_i8 v[122:125], v[154:157], v[198:201], v[122:125]
	v_mfma_i32_16x16x64_i8 v[102:105], v[150:153], v[202:205], v[102:105]
	v_mfma_i32_16x16x64_i8 v[102:105], v[154:157], v[206:209], v[102:105]
	v_mfma_i32_16x16x64_i8 v[86:89], v[150:153], v[224:227], v[86:89]
	v_mfma_i32_16x16x64_i8 v[86:89], v[154:157], v[228:231], v[86:89]
	v_mfma_i32_16x16x64_i8 v[70:73], v[150:153], v[232:235], v[70:73]
	v_mfma_i32_16x16x64_i8 v[70:73], v[154:157], v[236:239], v[70:73]
	v_mfma_i32_16x16x64_i8 v[118:121], v[158:161], v[194:197], v[118:121]
	v_mfma_i32_16x16x64_i8 v[118:121], v[174:177], v[198:201], v[118:121]
	v_mfma_i32_16x16x64_i8 v[106:109], v[158:161], v[202:205], v[106:109]
	v_mfma_i32_16x16x64_i8 v[106:109], v[174:177], v[206:209], v[106:109]
	v_mfma_i32_16x16x64_i8 v[90:93], v[158:161], v[224:227], v[90:93]
	v_mfma_i32_16x16x64_i8 v[90:93], v[174:177], v[228:231], v[90:93]
	v_mfma_i32_16x16x64_i8 v[74:77], v[158:161], v[232:235], v[74:77]
	v_mfma_i32_16x16x64_i8 v[74:77], v[174:177], v[236:239], v[74:77]
	v_mfma_i32_16x16x64_i8 v[114:117], v[186:189], v[194:197], v[114:117]
	v_mfma_i32_16x16x64_i8 v[114:117], v[190:193], v[198:201], v[114:117]
	v_mfma_i32_16x16x64_i8 v[98:101], v[186:189], v[202:205], v[98:101]
	v_mfma_i32_16x16x64_i8 v[98:101], v[190:193], v[206:209], v[98:101]
	v_mfma_i32_16x16x64_i8 v[82:85], v[186:189], v[224:227], v[82:85]
	v_mfma_i32_16x16x64_i8 v[82:85], v[190:193], v[228:231], v[82:85]
	v_mfma_i32_16x16x64_i8 v[66:69], v[186:189], v[232:235], v[66:69]
	v_mfma_i32_16x16x64_i8 v[66:69], v[190:193], v[236:239], v[66:69]
	s_setprio 0
	s_barrier
	s_add_i32 s20, s51, s33
	v_lshl_add_u64 v[162:163], v[162:163], 0, s[30:31]
	s_mov_b32 m0, s20
	ds_read_b128 v[194:197], v184 offset:49152
	ds_read_b128 v[198:201], v184 offset:50176
	ds_read_b128 v[202:205], v184 offset:51200
	ds_read_b128 v[206:209], v184 offset:52224
	ds_read_b128 v[224:227], v184 offset:53248
	ds_read_b128 v[228:231], v184 offset:54272
	ds_read_b128 v[232:235], v184 offset:55296
	ds_read_b128 v[236:239], v184 offset:56320
	global_load_lds_dwordx4 v[162:163], off
	s_add_i32 m0, s20, 0x2000
	s_add_u32 s16, s16, 0x40080
	v_lshl_add_u64 v[162:163], v[164:165], 0, s[30:31]
	s_addc_u32 s17, s17, 0
	s_add_i32 s20, s52, s33
	global_load_lds_dwordx4 v[162:163], off
	s_mov_b32 m0, s20
	s_nop 0
	global_load_lds_dwordx4 v0, s[16:17]
	s_add_i32 m0, s20, 0x2000
	s_nop 0
	global_load_lds_dwordx4 v138, s[16:17]
	v_lshl_add_u64 v[162:163], v[166:167], 0, s[30:31]
	s_mov_b32 m0, s34
	s_nop 0
	global_load_lds_dwordx4 v[162:163], off
	v_lshl_add_u64 v[162:163], v[168:169], 0, s[30:31]
	s_mov_b32 m0, s35
	s_nop 0
	global_load_lds_dwordx4 v[162:163], off
	s_waitcnt vmcnt(8)
	s_waitcnt lgkmcnt(0)
	s_barrier
	s_setprio 1
	s_waitcnt lgkmcnt(0)
	v_mfma_i32_16x16x64_i8 v[62:65], v[130:133], v[194:197], v[62:65]
	v_mfma_i32_16x16x64_i8 v[62:65], v[134:137], v[198:201], v[62:65]
	v_mfma_i32_16x16x64_i8 v[46:49], v[130:133], v[202:205], v[46:49]
	v_mfma_i32_16x16x64_i8 v[46:49], v[134:137], v[206:209], v[46:49]
	v_mfma_i32_16x16x64_i8 v[30:33], v[130:133], v[224:227], v[30:33]
	v_mfma_i32_16x16x64_i8 v[30:33], v[134:137], v[228:231], v[30:33]
	v_mfma_i32_16x16x64_i8 v[14:17], v[130:133], v[232:235], v[14:17]
	v_mfma_i32_16x16x64_i8 v[14:17], v[134:137], v[236:239], v[14:17]
	v_mfma_i32_16x16x64_i8 v[54:57], v[150:153], v[194:197], v[54:57]
	v_mfma_i32_16x16x64_i8 v[54:57], v[154:157], v[198:201], v[54:57]
	v_mfma_i32_16x16x64_i8 v[38:41], v[150:153], v[202:205], v[38:41]
	v_mfma_i32_16x16x64_i8 v[38:41], v[154:157], v[206:209], v[38:41]
	v_mfma_i32_16x16x64_i8 v[22:25], v[150:153], v[224:227], v[22:25]
	v_mfma_i32_16x16x64_i8 v[22:25], v[154:157], v[228:231], v[22:25]
	v_mfma_i32_16x16x64_i8 v[6:9], v[150:153], v[232:235], v[6:9]
	v_mfma_i32_16x16x64_i8 v[6:9], v[154:157], v[236:239], v[6:9]
	v_mfma_i32_16x16x64_i8 v[58:61], v[158:161], v[194:197], v[58:61]
	v_mfma_i32_16x16x64_i8 v[58:61], v[174:177], v[198:201], v[58:61]
	v_mfma_i32_16x16x64_i8 v[42:45], v[158:161], v[202:205], v[42:45]
	v_mfma_i32_16x16x64_i8 v[42:45], v[174:177], v[206:209], v[42:45]
	v_mfma_i32_16x16x64_i8 v[26:29], v[158:161], v[224:227], v[26:29]
	v_mfma_i32_16x16x64_i8 v[26:29], v[174:177], v[228:231], v[26:29]
	v_mfma_i32_16x16x64_i8 v[10:13], v[158:161], v[232:235], v[10:13]
	v_mfma_i32_16x16x64_i8 v[10:13], v[174:177], v[236:239], v[10:13]
	v_mfma_i32_16x16x64_i8 v[50:53], v[186:189], v[194:197], v[50:53]
	v_mfma_i32_16x16x64_i8 v[50:53], v[190:193], v[198:201], v[50:53]
	v_mfma_i32_16x16x64_i8 v[34:37], v[186:189], v[202:205], v[34:37]
	v_mfma_i32_16x16x64_i8 v[34:37], v[190:193], v[206:209], v[34:37]
	v_mfma_i32_16x16x64_i8 v[18:21], v[186:189], v[224:227], v[18:21]
	v_mfma_i32_16x16x64_i8 v[18:21], v[190:193], v[228:231], v[18:21]
	v_mfma_i32_16x16x64_i8 v[2:5], v[186:189], v[232:235], v[2:5]
	v_mfma_i32_16x16x64_i8 v[2:5], v[190:193], v[236:239], v[2:5]
	s_setprio 0
	s_barrier
	s_add_i32 s50, s50, 2
	s_add_u32 s14, s14, 0x100
	s_addc_u32 s15, s15, 0
	s_add_u32 s48, s48, 0x100
	s_addc_u32 s49, s49, 0
	s_cmp_gt_u32 s50, 13
	s_cbranch_scc0 .LBB0_411
	v_readlane_b32 s14, v253, 2
	v_readlane_b32 s15, v253, 3
	s_and_b64 vcc, exec, s[14:15]
	s_cbranch_vccz .LBB0_414
	s_barrier

.LBB0_493:
	s_add_u32 s16, s12, 0x100
	s_addc_u32 s17, s13, 0
	s_add_i32 s67, 0, 0x10000
	s_cmpk_eq_i32 s19, 0x54
	s_cselect_b32 s23, s7, s17
	s_cselect_b32 s22, s6, s16
	s_cselect_b32 s21, s11, s18
	s_cselect_b32 s20, s10, s15
	s_add_i32 s68, 0, 0x14000
	v_add_u32_e32 v142, s67, v205
	v_add_u32_e32 v162, s68, v205
	ds_read_b128 v[130:133], v142
	ds_read_b128 v[134:137], v142 offset:1024
	ds_read_b128 v[138:141], v142 offset:2048
	ds_read_b128 v[142:145], v142 offset:3072
	ds_read_b128 v[146:149], v162
	ds_read_b128 v[150:153], v162 offset:1024
	ds_read_b128 v[154:157], v162 offset:2048
	ds_read_b128 v[184:187], v162 offset:3072
	s_add_i32 m0, s28, 0xc000
	ds_read_b128 v[188:191], v230
	ds_read_b128 v[192:195], v230 offset:1024
	ds_read_b128 v[196:199], v230 offset:2048
	ds_read_b128 v[200:203], v230 offset:3072
	ds_read_b128 v[232:235], v230 offset:4096
	ds_read_b128 v[236:239], v230 offset:5120
	ds_read_b128 v[240:243], v230 offset:6144
	ds_read_b128 v[244:247], v230 offset:7168
	global_load_lds_dwordx4 v180, s[12:13]
	s_add_i32 m0, s28, 0xe000
	s_nop 0
	global_load_lds_dwordx4 v182, s[12:13]
	s_waitcnt vmcnt(8)
	s_waitcnt lgkmcnt(0)
	s_barrier
	s_setprio 1
	s_waitcnt lgkmcnt(0)
	v_mfma_f32_16x16x32_bf16 v[126:129], v[130:133], v[188:191], v[126:129]
	v_mfma_f32_16x16x32_bf16 v[126:129], v[134:137], v[192:195], v[126:129]
	v_mfma_f32_16x16x32_bf16 v[118:121], v[130:133], v[196:199], v[118:121]
	v_mfma_f32_16x16x32_bf16 v[118:121], v[134:137], v[200:203], v[118:121]
	v_mfma_f32_16x16x32_bf16 v[110:113], v[130:133], v[232:235], v[110:113]
	v_mfma_f32_16x16x32_bf16 v[110:113], v[134:137], v[236:239], v[110:113]
	v_mfma_f32_16x16x32_bf16 v[102:105], v[130:133], v[240:243], v[102:105]
	v_mfma_f32_16x16x32_bf16 v[102:105], v[134:137], v[244:247], v[102:105]
	v_mfma_f32_16x16x32_bf16 v[74:77], v[138:141], v[188:191], v[74:77]
	v_mfma_f32_16x16x32_bf16 v[74:77], v[142:145], v[192:195], v[74:77]
	v_mfma_f32_16x16x32_bf16 v[86:89], v[138:141], v[196:199], v[86:89]
	v_mfma_f32_16x16x32_bf16 v[86:89], v[142:145], v[200:203], v[86:89]
	v_mfma_f32_16x16x32_bf16 v[66:69], v[138:141], v[232:235], v[66:69]
	v_mfma_f32_16x16x32_bf16 v[66:69], v[142:145], v[236:239], v[66:69]
	v_mfma_f32_16x16x32_bf16 v[38:41], v[138:141], v[240:243], v[38:41]
	v_mfma_f32_16x16x32_bf16 v[38:41], v[142:145], v[244:247], v[38:41]
	v_mfma_f32_16x16x32_bf16 v[122:125], v[146:149], v[188:191], v[122:125]
	v_mfma_f32_16x16x32_bf16 v[122:125], v[150:153], v[192:195], v[122:125]
	v_mfma_f32_16x16x32_bf16 v[114:117], v[146:149], v[196:199], v[114:117]
	v_mfma_f32_16x16x32_bf16 v[114:117], v[150:153], v[200:203], v[114:117]
	v_mfma_f32_16x16x32_bf16 v[106:109], v[146:149], v[232:235], v[106:109]
	v_mfma_f32_16x16x32_bf16 v[106:109], v[150:153], v[236:239], v[106:109]
	v_mfma_f32_16x16x32_bf16 v[98:101], v[146:149], v[240:243], v[98:101]
	v_mfma_f32_16x16x32_bf16 v[98:101], v[150:153], v[244:247], v[98:101]
	v_mfma_f32_16x16x32_bf16 v[82:85], v[154:157], v[188:191], v[82:85]
	v_mfma_f32_16x16x32_bf16 v[82:85], v[184:187], v[192:195], v[82:85]
	v_mfma_f32_16x16x32_bf16 v[90:93], v[154:157], v[196:199], v[90:93]
	v_mfma_f32_16x16x32_bf16 v[90:93], v[184:187], v[200:203], v[90:93]
	v_mfma_f32_16x16x32_bf16 v[70:73], v[154:157], v[232:235], v[70:73]
	v_mfma_f32_16x16x32_bf16 v[70:73], v[184:187], v[236:239], v[70:73]
	v_mfma_f32_16x16x32_bf16 v[42:45], v[154:157], v[240:243], v[42:45]
	v_mfma_f32_16x16x32_bf16 v[42:45], v[184:187], v[244:247], v[42:45]
	s_setprio 0
	s_barrier
	s_add_i32 s12, s67, s33
	v_lshl_add_u64 v[162:163], s[20:21], 0, v[0:1]
	s_mov_b32 m0, s12
	ds_read_b128 v[188:191], v230 offset:16384
	ds_read_b128 v[192:195], v230 offset:17408
	ds_read_b128 v[196:199], v230 offset:18432
	ds_read_b128 v[200:203], v230 offset:19456
	ds_read_b128 v[232:235], v230 offset:20480
	ds_read_b128 v[236:239], v230 offset:21504
	ds_read_b128 v[240:243], v230 offset:22528
	ds_read_b128 v[244:247], v230 offset:23552
	global_load_lds_dwordx4 v[162:163], off
	s_add_i32 m0, s12, 0x2000
	s_add_u32 s12, s20, 0x160000
	v_lshl_add_u64 v[164:165], s[20:21], 0, v[158:159]
	s_addc_u32 s13, s21, 0
	s_add_i32 s67, s68, s33
	global_load_lds_dwordx4 v[164:165], off
	s_mov_b32 m0, s67
	v_lshl_add_u64 v[168:169], s[22:23], 0, v[160:161]
	global_load_lds_dwordx4 v0, s[12:13]
	s_add_i32 m0, s67, 0x2000
	s_nop 0
	global_load_lds_dwordx4 v158, s[12:13]
	v_lshl_add_u64 v[166:167], s[22:23], 0, v[174:175]
	s_mov_b32 m0, s28
	s_nop 0
	global_load_lds_dwordx4 v[166:167], off
	s_mov_b32 m0, s29
	s_nop 0
	global_load_lds_dwordx4 v[168:169], off
	s_waitcnt vmcnt(8)
	s_waitcnt lgkmcnt(0)
	s_barrier
	s_setprio 1
	s_waitcnt lgkmcnt(0)
	v_mfma_f32_16x16x32_bf16 v[94:97], v[130:133], v[188:191], v[94:97]
	v_mfma_f32_16x16x32_bf16 v[94:97], v[134:137], v[192:195], v[94:97]
	v_mfma_f32_16x16x32_bf16 v[62:65], v[130:133], v[196:199], v[62:65]
	v_mfma_f32_16x16x32_bf16 v[62:65], v[134:137], v[200:203], v[62:65]
	v_mfma_f32_16x16x32_bf16 v[46:49], v[130:133], v[232:235], v[46:49]
	v_mfma_f32_16x16x32_bf16 v[46:49], v[134:137], v[236:239], v[46:49]
	v_mfma_f32_16x16x32_bf16 v[22:25], v[130:133], v[240:243], v[22:25]
	v_mfma_f32_16x16x32_bf16 v[22:25], v[134:137], v[244:247], v[22:25]
	v_mfma_f32_16x16x32_bf16 v[50:53], v[138:141], v[188:191], v[50:53]
	v_mfma_f32_16x16x32_bf16 v[50:53], v[142:145], v[192:195], v[50:53]
	v_mfma_f32_16x16x32_bf16 v[30:33], v[138:141], v[196:199], v[30:33]
	v_mfma_f32_16x16x32_bf16 v[30:33], v[142:145], v[200:203], v[30:33]
	v_mfma_f32_16x16x32_bf16 v[10:13], v[138:141], v[232:235], v[10:13]
	v_mfma_f32_16x16x32_bf16 v[10:13], v[142:145], v[236:239], v[10:13]
	v_mfma_f32_16x16x32_bf16 v[2:5], v[138:141], v[240:243], v[2:5]
	v_mfma_f32_16x16x32_bf16 v[2:5], v[142:145], v[244:247], v[2:5]
	v_mfma_f32_16x16x32_bf16 v[78:81], v[146:149], v[188:191], v[78:81]
	v_mfma_f32_16x16x32_bf16 v[78:81], v[150:153], v[192:195], v[78:81]
	v_mfma_f32_16x16x32_bf16 v[54:57], v[146:149], v[196:199], v[54:57]
	v_mfma_f32_16x16x32_bf16 v[54:57], v[150:153], v[200:203], v[54:57]
	v_mfma_f32_16x16x32_bf16 v[26:29], v[146:149], v[232:235], v[26:29]
	v_mfma_f32_16x16x32_bf16 v[26:29], v[150:153], v[236:239], v[26:29]
	v_mfma_f32_16x16x32_bf16 v[18:21], v[146:149], v[240:243], v[18:21]
	v_mfma_f32_16x16x32_bf16 v[18:21], v[150:153], v[244:247], v[18:21]
	v_mfma_f32_16x16x32_bf16 v[58:61], v[154:157], v[188:191], v[58:61]
	v_mfma_f32_16x16x32_bf16 v[58:61], v[184:187], v[192:195], v[58:61]
	v_mfma_f32_16x16x32_bf16 v[34:37], v[154:157], v[196:199], v[34:37]
	v_mfma_f32_16x16x32_bf16 v[34:37], v[184:187], v[200:203], v[34:37]
	v_mfma_f32_16x16x32_bf16 v[14:17], v[154:157], v[232:235], v[14:17]
	v_mfma_f32_16x16x32_bf16 v[14:17], v[184:187], v[236:239], v[14:17]
	v_mfma_f32_16x16x32_bf16 v[6:9], v[154:157], v[240:243], v[6:9]
	v_mfma_f32_16x16x32_bf16 v[6:9], v[184:187], v[244:247], v[6:9]
	s_setprio 0
	s_barrier
	s_add_i32 s67, 0, 0x18000
	s_add_i32 s68, 0, 0x1c000
	v_add_u32_e32 v142, s67, v205
	v_add_u32_e32 v170, s68, v205
	ds_read_b128 v[130:133], v142
	ds_read_b128 v[134:137], v142 offset:1024
	ds_read_b128 v[138:141], v142 offset:2048
	ds_read_b128 v[142:145], v142 offset:3072
	ds_read_b128 v[146:149], v170
	ds_read_b128 v[150:153], v170 offset:1024
	ds_read_b128 v[154:157], v170 offset:2048
	ds_read_b128 v[184:187], v170 offset:3072
	s_add_u32 s12, s22, 0x160000
	s_addc_u32 s13, s23, 0
	s_mov_b32 m0, s34
	ds_read_b128 v[188:191], v230 offset:32768
	ds_read_b128 v[192:195], v230 offset:33792
	ds_read_b128 v[196:199], v230 offset:34816
	ds_read_b128 v[200:203], v230 offset:35840
	ds_read_b128 v[232:235], v230 offset:36864
	ds_read_b128 v[236:239], v230 offset:37888
	ds_read_b128 v[240:243], v230 offset:38912
	ds_read_b128 v[244:247], v230 offset:39936
	global_load_lds_dwordx4 v174, s[12:13]
	s_mov_b32 m0, s35
	s_nop 0
	global_load_lds_dwordx4 v160, s[12:13]
	s_waitcnt vmcnt(8)
	s_waitcnt lgkmcnt(0)
	s_barrier
	s_setprio 1
	s_waitcnt lgkmcnt(0)
	v_mfma_f32_16x16x32_bf16 v[126:129], v[130:133], v[188:191], v[126:129]
	v_mfma_f32_16x16x32_bf16 v[126:129], v[134:137], v[192:195], v[126:129]
	v_mfma_f32_16x16x32_bf16 v[118:121], v[130:133], v[196:199], v[118:121]
	v_mfma_f32_16x16x32_bf16 v[118:121], v[134:137], v[200:203], v[118:121]
	v_mfma_f32_16x16x32_bf16 v[110:113], v[130:133], v[232:235], v[110:113]
	v_mfma_f32_16x16x32_bf16 v[110:113], v[134:137], v[236:239], v[110:113]
	v_mfma_f32_16x16x32_bf16 v[102:105], v[130:133], v[240:243], v[102:105]
	v_mfma_f32_16x16x32_bf16 v[102:105], v[134:137], v[244:247], v[102:105]
	v_mfma_f32_16x16x32_bf16 v[74:77], v[138:141], v[188:191], v[74:77]
	v_mfma_f32_16x16x32_bf16 v[74:77], v[142:145], v[192:195], v[74:77]
	v_mfma_f32_16x16x32_bf16 v[86:89], v[138:141], v[196:199], v[86:89]
	v_mfma_f32_16x16x32_bf16 v[86:89], v[142:145], v[200:203], v[86:89]
	v_mfma_f32_16x16x32_bf16 v[66:69], v[138:141], v[232:235], v[66:69]
	v_mfma_f32_16x16x32_bf16 v[66:69], v[142:145], v[236:239], v[66:69]
	v_mfma_f32_16x16x32_bf16 v[38:41], v[138:141], v[240:243], v[38:41]
	v_mfma_f32_16x16x32_bf16 v[38:41], v[142:145], v[244:247], v[38:41]
	v_mfma_f32_16x16x32_bf16 v[122:125], v[146:149], v[188:191], v[122:125]
	v_mfma_f32_16x16x32_bf16 v[122:125], v[150:153], v[192:195], v[122:125]
	v_mfma_f32_16x16x32_bf16 v[114:117], v[146:149], v[196:199], v[114:117]
	v_mfma_f32_16x16x32_bf16 v[114:117], v[150:153], v[200:203], v[114:117]
	v_mfma_f32_16x16x32_bf16 v[106:109], v[146:149], v[232:235], v[106:109]
	v_mfma_f32_16x16x32_bf16 v[106:109], v[150:153], v[236:239], v[106:109]
	v_mfma_f32_16x16x32_bf16 v[98:101], v[146:149], v[240:243], v[98:101]
	v_mfma_f32_16x16x32_bf16 v[98:101], v[150:153], v[244:247], v[98:101]
	v_mfma_f32_16x16x32_bf16 v[82:85], v[154:157], v[188:191], v[82:85]
	v_mfma_f32_16x16x32_bf16 v[82:85], v[184:187], v[192:195], v[82:85]
	v_mfma_f32_16x16x32_bf16 v[90:93], v[154:157], v[196:199], v[90:93]
	v_mfma_f32_16x16x32_bf16 v[90:93], v[184:187], v[200:203], v[90:93]
	v_mfma_f32_16x16x32_bf16 v[70:73], v[154:157], v[232:235], v[70:73]
	v_mfma_f32_16x16x32_bf16 v[70:73], v[184:187], v[236:239], v[70:73]
	v_mfma_f32_16x16x32_bf16 v[42:45], v[154:157], v[240:243], v[42:45]
	v_mfma_f32_16x16x32_bf16 v[42:45], v[184:187], v[244:247], v[42:45]
	s_setprio 0
	s_barrier
	s_add_i32 s12, s67, s33
	v_lshl_add_u64 v[162:163], v[162:163], 0, s[30:31]
	s_mov_b32 m0, s12
	ds_read_b128 v[188:191], v230 offset:49152
	ds_read_b128 v[192:195], v230 offset:50176
	ds_read_b128 v[196:199], v230 offset:51200
	ds_read_b128 v[200:203], v230 offset:52224
	ds_read_b128 v[232:235], v230 offset:53248
	ds_read_b128 v[236:239], v230 offset:54272
	ds_read_b128 v[240:243], v230 offset:55296
	ds_read_b128 v[244:247], v230 offset:56320
	global_load_lds_dwordx4 v[162:163], off
	s_add_i32 m0, s12, 0x2000
	s_add_u32 s12, s20, 0x160080
	v_lshl_add_u64 v[162:163], v[164:165], 0, s[30:31]
	s_addc_u32 s13, s21, 0
	s_add_i32 s20, s68, s33
	global_load_lds_dwordx4 v[162:163], off
	s_mov_b32 m0, s20
	s_nop 0
	global_load_lds_dwordx4 v0, s[12:13]
	s_add_i32 m0, s20, 0x2000
	s_nop 0
	global_load_lds_dwordx4 v158, s[12:13]
	v_lshl_add_u64 v[162:163], v[166:167], 0, s[30:31]
	s_mov_b32 m0, s55
	s_nop 0
	global_load_lds_dwordx4 v[162:163], off
	v_lshl_add_u64 v[162:163], v[168:169], 0, s[30:31]
	s_mov_b32 m0, s56
	s_nop 0
	global_load_lds_dwordx4 v[162:163], off
	s_waitcnt vmcnt(8)
	s_waitcnt lgkmcnt(0)
	s_barrier
	s_setprio 1
	s_waitcnt lgkmcnt(0)
	v_mfma_f32_16x16x32_bf16 v[94:97], v[130:133], v[188:191], v[94:97]
	v_mfma_f32_16x16x32_bf16 v[94:97], v[134:137], v[192:195], v[94:97]
	v_mfma_f32_16x16x32_bf16 v[62:65], v[130:133], v[196:199], v[62:65]
	v_mfma_f32_16x16x32_bf16 v[62:65], v[134:137], v[200:203], v[62:65]
	v_mfma_f32_16x16x32_bf16 v[46:49], v[130:133], v[232:235], v[46:49]
	v_mfma_f32_16x16x32_bf16 v[46:49], v[134:137], v[236:239], v[46:49]
	v_mfma_f32_16x16x32_bf16 v[22:25], v[130:133], v[240:243], v[22:25]
	v_mfma_f32_16x16x32_bf16 v[22:25], v[134:137], v[244:247], v[22:25]
	v_mfma_f32_16x16x32_bf16 v[50:53], v[138:141], v[188:191], v[50:53]
	v_mfma_f32_16x16x32_bf16 v[50:53], v[142:145], v[192:195], v[50:53]
	v_mfma_f32_16x16x32_bf16 v[30:33], v[138:141], v[196:199], v[30:33]
	v_mfma_f32_16x16x32_bf16 v[30:33], v[142:145], v[200:203], v[30:33]
	v_mfma_f32_16x16x32_bf16 v[10:13], v[138:141], v[232:235], v[10:13]
	v_mfma_f32_16x16x32_bf16 v[10:13], v[142:145], v[236:239], v[10:13]
	v_mfma_f32_16x16x32_bf16 v[2:5], v[138:141], v[240:243], v[2:5]
	v_mfma_f32_16x16x32_bf16 v[2:5], v[142:145], v[244:247], v[2:5]
	v_mfma_f32_16x16x32_bf16 v[78:81], v[146:149], v[188:191], v[78:81]
	v_mfma_f32_16x16x32_bf16 v[78:81], v[150:153], v[192:195], v[78:81]
	v_mfma_f32_16x16x32_bf16 v[54:57], v[146:149], v[196:199], v[54:57]
	v_mfma_f32_16x16x32_bf16 v[54:57], v[150:153], v[200:203], v[54:57]
	v_mfma_f32_16x16x32_bf16 v[26:29], v[146:149], v[232:235], v[26:29]
	v_mfma_f32_16x16x32_bf16 v[26:29], v[150:153], v[236:239], v[26:29]
	v_mfma_f32_16x16x32_bf16 v[18:21], v[146:149], v[240:243], v[18:21]
	v_mfma_f32_16x16x32_bf16 v[18:21], v[150:153], v[244:247], v[18:21]
	v_mfma_f32_16x16x32_bf16 v[58:61], v[154:157], v[188:191], v[58:61]
	v_mfma_f32_16x16x32_bf16 v[58:61], v[184:187], v[192:195], v[58:61]
	v_mfma_f32_16x16x32_bf16 v[34:37], v[154:157], v[196:199], v[34:37]
	v_mfma_f32_16x16x32_bf16 v[34:37], v[184:187], v[200:203], v[34:37]
	v_mfma_f32_16x16x32_bf16 v[14:17], v[154:157], v[232:235], v[14:17]
	v_mfma_f32_16x16x32_bf16 v[14:17], v[184:187], v[236:239], v[14:17]
	v_mfma_f32_16x16x32_bf16 v[6:9], v[154:157], v[240:243], v[6:9]
	v_mfma_f32_16x16x32_bf16 v[6:9], v[184:187], v[244:247], v[6:9]
	s_setprio 0
	s_barrier
	s_add_i32 s19, s19, 2
	s_add_u32 s15, s15, 0x100
	s_addc_u32 s18, s18, 0
	s_cmpk_gt_u32 s19, 0x55
	s_mov_b64 s[12:13], s[16:17]
	s_cbranch_scc0 .LBB0_493
	v_readlane_b32 s12, v253, 2
	v_readlane_b32 s13, v253, 3
	s_and_b64 vcc, exec, s[12:13]
	s_cbranch_vccz .LBB0_496
	s_barrier

.LBB0_641:
	s_add_u32 s28, s26, 0xfffc0080
	s_addc_u32 s29, s27, -1
	s_add_i32 s57, 0, 0x10000
	s_cmp_eq_u32 s56, 12
	s_cselect_b32 s43, s15, s29
	s_cselect_b32 s42, s19, s28
	s_cselect_b32 s29, s11, s55
	s_cselect_b32 s28, s53, s54
	s_add_i32 s60, 0, 0x14000
	v_add_u32_e32 v152, s57, v159
	v_add_u32_e32 v156, s60, v159
	ds_read_b128 v[140:143], v152
	ds_read_b128 v[144:147], v152 offset:1024
	ds_read_b128 v[148:151], v152 offset:2048
	ds_read_b128 v[152:155], v152 offset:3072
	ds_read_b128 v[176:179], v156
	ds_read_b128 v[180:183], v156 offset:1024
	ds_read_b128 v[184:187], v156 offset:2048
	ds_read_b128 v[188:191], v156 offset:3072
	s_add_i32 m0, s44, 0xc000
	ds_read_b128 v[192:195], v174
	ds_read_b128 v[196:199], v174 offset:1024
	ds_read_b128 v[200:203], v174 offset:2048
	ds_read_b128 v[204:207], v174 offset:3072
	ds_read_b128 v[208:211], v174 offset:4096
	ds_read_b128 v[224:227], v174 offset:5120
	ds_read_b128 v[228:231], v174 offset:6144
	ds_read_b128 v[232:235], v174 offset:7168
	global_load_lds_dwordx4 v136, s[26:27]
	s_add_i32 m0, s44, 0xe000
	s_nop 0
	global_load_lds_dwordx4 v138, s[26:27]
	s_waitcnt vmcnt(8)
	s_waitcnt lgkmcnt(0)
	s_barrier
	s_setprio 1
	s_waitcnt lgkmcnt(0)
	v_mfma_i32_16x16x64_i8 v[126:129], v[140:143], v[192:195], v[126:129]
	v_mfma_i32_16x16x64_i8 v[126:129], v[144:147], v[196:199], v[126:129]
	v_mfma_i32_16x16x64_i8 v[110:113], v[140:143], v[200:203], v[110:113]
	v_mfma_i32_16x16x64_i8 v[110:113], v[144:147], v[204:207], v[110:113]
	v_mfma_i32_16x16x64_i8 v[94:97], v[140:143], v[208:211], v[94:97]
	v_mfma_i32_16x16x64_i8 v[94:97], v[144:147], v[224:227], v[94:97]
	v_mfma_i32_16x16x64_i8 v[78:81], v[140:143], v[228:231], v[78:81]
	v_mfma_i32_16x16x64_i8 v[78:81], v[144:147], v[232:235], v[78:81]
	v_mfma_i32_16x16x64_i8 v[122:125], v[148:151], v[192:195], v[122:125]
	v_mfma_i32_16x16x64_i8 v[122:125], v[152:155], v[196:199], v[122:125]
	v_mfma_i32_16x16x64_i8 v[106:109], v[148:151], v[200:203], v[106:109]
	v_mfma_i32_16x16x64_i8 v[106:109], v[152:155], v[204:207], v[106:109]
	v_mfma_i32_16x16x64_i8 v[90:93], v[148:151], v[208:211], v[90:93]
	v_mfma_i32_16x16x64_i8 v[90:93], v[152:155], v[224:227], v[90:93]
	v_mfma_i32_16x16x64_i8 v[74:77], v[148:151], v[228:231], v[74:77]
	v_mfma_i32_16x16x64_i8 v[74:77], v[152:155], v[232:235], v[74:77]
	v_mfma_i32_16x16x64_i8 v[118:121], v[176:179], v[192:195], v[118:121]
	v_mfma_i32_16x16x64_i8 v[118:121], v[180:183], v[196:199], v[118:121]
	v_mfma_i32_16x16x64_i8 v[102:105], v[176:179], v[200:203], v[102:105]
	v_mfma_i32_16x16x64_i8 v[102:105], v[180:183], v[204:207], v[102:105]
	v_mfma_i32_16x16x64_i8 v[86:89], v[176:179], v[208:211], v[86:89]
	v_mfma_i32_16x16x64_i8 v[86:89], v[180:183], v[224:227], v[86:89]
	v_mfma_i32_16x16x64_i8 v[70:73], v[176:179], v[228:231], v[70:73]
	v_mfma_i32_16x16x64_i8 v[70:73], v[180:183], v[232:235], v[70:73]
	v_mfma_i32_16x16x64_i8 v[114:117], v[184:187], v[192:195], v[114:117]
	v_mfma_i32_16x16x64_i8 v[114:117], v[188:191], v[196:199], v[114:117]
	v_mfma_i32_16x16x64_i8 v[98:101], v[184:187], v[200:203], v[98:101]
	v_mfma_i32_16x16x64_i8 v[98:101], v[188:191], v[204:207], v[98:101]
	v_mfma_i32_16x16x64_i8 v[82:85], v[184:187], v[208:211], v[82:85]
	v_mfma_i32_16x16x64_i8 v[82:85], v[188:191], v[224:227], v[82:85]
	v_mfma_i32_16x16x64_i8 v[66:69], v[184:187], v[228:231], v[66:69]
	v_mfma_i32_16x16x64_i8 v[66:69], v[188:191], v[232:235], v[66:69]
	s_setprio 0
	s_barrier
	s_add_i32 s57, s57, s33
	v_lshl_add_u64 v[156:157], s[28:29], 0, v[0:1]
	s_mov_b32 m0, s57
	ds_read_b128 v[192:195], v174 offset:16384
	ds_read_b128 v[196:199], v174 offset:17408
	ds_read_b128 v[200:203], v174 offset:18432
	ds_read_b128 v[204:207], v174 offset:19456
	ds_read_b128 v[208:211], v174 offset:20480
	ds_read_b128 v[224:227], v174 offset:21504
	ds_read_b128 v[228:231], v174 offset:22528
	ds_read_b128 v[232:235], v174 offset:23552
	global_load_lds_dwordx4 v[156:157], off
	s_add_i32 m0, s57, 0x2000
	s_add_u32 s58, s28, 0x40000
	v_lshl_add_u64 v[162:163], s[28:29], 0, v[130:131]
	s_addc_u32 s59, s29, 0
	s_add_i32 s57, s60, s33
	global_load_lds_dwordx4 v[162:163], off
	s_mov_b32 m0, s57
	v_lshl_add_u64 v[166:167], s[42:43], 0, v[132:133]
	global_load_lds_dwordx4 v0, s[58:59]
	s_add_i32 m0, s57, 0x2000
	s_nop 0
	global_load_lds_dwordx4 v130, s[58:59]
	v_lshl_add_u64 v[164:165], s[42:43], 0, v[134:135]
	s_mov_b32 m0, s44
	s_nop 0
	global_load_lds_dwordx4 v[164:165], off
	s_mov_b32 m0, s45
	s_nop 0
	global_load_lds_dwordx4 v[166:167], off
	s_waitcnt vmcnt(8)
	s_waitcnt lgkmcnt(0)
	s_barrier
	s_setprio 1
	s_waitcnt lgkmcnt(0)
	v_mfma_i32_16x16x64_i8 v[62:65], v[140:143], v[192:195], v[62:65]
	v_mfma_i32_16x16x64_i8 v[62:65], v[144:147], v[196:199], v[62:65]
	v_mfma_i32_16x16x64_i8 v[46:49], v[140:143], v[200:203], v[46:49]
	v_mfma_i32_16x16x64_i8 v[46:49], v[144:147], v[204:207], v[46:49]
	v_mfma_i32_16x16x64_i8 v[30:33], v[140:143], v[208:211], v[30:33]
	v_mfma_i32_16x16x64_i8 v[30:33], v[144:147], v[224:227], v[30:33]
	v_mfma_i32_16x16x64_i8 v[14:17], v[140:143], v[228:231], v[14:17]
	v_mfma_i32_16x16x64_i8 v[14:17], v[144:147], v[232:235], v[14:17]
	v_mfma_i32_16x16x64_i8 v[58:61], v[148:151], v[192:195], v[58:61]
	v_mfma_i32_16x16x64_i8 v[58:61], v[152:155], v[196:199], v[58:61]
	v_mfma_i32_16x16x64_i8 v[42:45], v[148:151], v[200:203], v[42:45]
	v_mfma_i32_16x16x64_i8 v[42:45], v[152:155], v[204:207], v[42:45]
	v_mfma_i32_16x16x64_i8 v[26:29], v[148:151], v[208:211], v[26:29]
	v_mfma_i32_16x16x64_i8 v[26:29], v[152:155], v[224:227], v[26:29]
	v_mfma_i32_16x16x64_i8 v[10:13], v[148:151], v[228:231], v[10:13]
	v_mfma_i32_16x16x64_i8 v[10:13], v[152:155], v[232:235], v[10:13]
	v_mfma_i32_16x16x64_i8 v[54:57], v[176:179], v[192:195], v[54:57]
	v_mfma_i32_16x16x64_i8 v[54:57], v[180:183], v[196:199], v[54:57]
	v_mfma_i32_16x16x64_i8 v[38:41], v[176:179], v[200:203], v[38:41]
	v_mfma_i32_16x16x64_i8 v[38:41], v[180:183], v[204:207], v[38:41]
	v_mfma_i32_16x16x64_i8 v[22:25], v[176:179], v[208:211], v[22:25]
	v_mfma_i32_16x16x64_i8 v[22:25], v[180:183], v[224:227], v[22:25]
	v_mfma_i32_16x16x64_i8 v[6:9], v[176:179], v[228:231], v[6:9]
	v_mfma_i32_16x16x64_i8 v[6:9], v[180:183], v[232:235], v[6:9]
	v_mfma_i32_16x16x64_i8 v[50:53], v[184:187], v[192:195], v[50:53]
	v_mfma_i32_16x16x64_i8 v[50:53], v[188:191], v[196:199], v[50:53]
	v_mfma_i32_16x16x64_i8 v[34:37], v[184:187], v[200:203], v[34:37]
	v_mfma_i32_16x16x64_i8 v[34:37], v[188:191], v[204:207], v[34:37]
	v_mfma_i32_16x16x64_i8 v[18:21], v[184:187], v[208:211], v[18:21]
	v_mfma_i32_16x16x64_i8 v[18:21], v[188:191], v[224:227], v[18:21]
	v_mfma_i32_16x16x64_i8 v[2:5], v[184:187], v[228:231], v[2:5]
	v_mfma_i32_16x16x64_i8 v[2:5], v[188:191], v[232:235], v[2:5]
	s_setprio 0
	s_barrier
	s_add_i32 s57, 0, 0x18000
	s_add_i32 s58, 0, 0x1c000
	v_add_u32_e32 v152, s57, v159
	v_add_u32_e32 v168, s58, v159
	ds_read_b128 v[140:143], v152
	ds_read_b128 v[144:147], v152 offset:1024
	ds_read_b128 v[148:151], v152 offset:2048
	ds_read_b128 v[152:155], v152 offset:3072
	ds_read_b128 v[176:179], v168
	ds_read_b128 v[180:183], v168 offset:1024
	ds_read_b128 v[184:187], v168 offset:2048
	ds_read_b128 v[188:191], v168 offset:3072
	s_add_u32 s42, s42, 0x40000
	s_addc_u32 s43, s43, 0
	s_mov_b32 m0, s46
	ds_read_b128 v[192:195], v174 offset:32768
	ds_read_b128 v[196:199], v174 offset:33792
	ds_read_b128 v[200:203], v174 offset:34816
	ds_read_b128 v[204:207], v174 offset:35840
	ds_read_b128 v[208:211], v174 offset:36864
	ds_read_b128 v[224:227], v174 offset:37888
	ds_read_b128 v[228:231], v174 offset:38912
	ds_read_b128 v[232:235], v174 offset:39936
	global_load_lds_dwordx4 v134, s[42:43]
	s_mov_b32 m0, s47
	s_nop 0
	global_load_lds_dwordx4 v132, s[42:43]
	s_waitcnt vmcnt(8)
	s_waitcnt lgkmcnt(0)
	s_barrier
	s_setprio 1
	s_waitcnt lgkmcnt(0)
	v_mfma_i32_16x16x64_i8 v[126:129], v[140:143], v[192:195], v[126:129]
	v_mfma_i32_16x16x64_i8 v[126:129], v[144:147], v[196:199], v[126:129]
	v_mfma_i32_16x16x64_i8 v[110:113], v[140:143], v[200:203], v[110:113]
	v_mfma_i32_16x16x64_i8 v[110:113], v[144:147], v[204:207], v[110:113]
	v_mfma_i32_16x16x64_i8 v[94:97], v[140:143], v[208:211], v[94:97]
	v_mfma_i32_16x16x64_i8 v[94:97], v[144:147], v[224:227], v[94:97]
	v_mfma_i32_16x16x64_i8 v[78:81], v[140:143], v[228:231], v[78:81]
	v_mfma_i32_16x16x64_i8 v[78:81], v[144:147], v[232:235], v[78:81]
	v_mfma_i32_16x16x64_i8 v[122:125], v[148:151], v[192:195], v[122:125]
	v_mfma_i32_16x16x64_i8 v[122:125], v[152:155], v[196:199], v[122:125]
	v_mfma_i32_16x16x64_i8 v[106:109], v[148:151], v[200:203], v[106:109]
	v_mfma_i32_16x16x64_i8 v[106:109], v[152:155], v[204:207], v[106:109]
	v_mfma_i32_16x16x64_i8 v[90:93], v[148:151], v[208:211], v[90:93]
	v_mfma_i32_16x16x64_i8 v[90:93], v[152:155], v[224:227], v[90:93]
	v_mfma_i32_16x16x64_i8 v[74:77], v[148:151], v[228:231], v[74:77]
	v_mfma_i32_16x16x64_i8 v[74:77], v[152:155], v[232:235], v[74:77]
	v_mfma_i32_16x16x64_i8 v[118:121], v[176:179], v[192:195], v[118:121]
	v_mfma_i32_16x16x64_i8 v[118:121], v[180:183], v[196:199], v[118:121]
	v_mfma_i32_16x16x64_i8 v[102:105], v[176:179], v[200:203], v[102:105]
	v_mfma_i32_16x16x64_i8 v[102:105], v[180:183], v[204:207], v[102:105]
	v_mfma_i32_16x16x64_i8 v[86:89], v[176:179], v[208:211], v[86:89]
	v_mfma_i32_16x16x64_i8 v[86:89], v[180:183], v[224:227], v[86:89]
	v_mfma_i32_16x16x64_i8 v[70:73], v[176:179], v[228:231], v[70:73]
	v_mfma_i32_16x16x64_i8 v[70:73], v[180:183], v[232:235], v[70:73]
	v_mfma_i32_16x16x64_i8 v[114:117], v[184:187], v[192:195], v[114:117]
	v_mfma_i32_16x16x64_i8 v[114:117], v[188:191], v[196:199], v[114:117]
	v_mfma_i32_16x16x64_i8 v[98:101], v[184:187], v[200:203], v[98:101]
	v_mfma_i32_16x16x64_i8 v[98:101], v[188:191], v[204:207], v[98:101]
	v_mfma_i32_16x16x64_i8 v[82:85], v[184:187], v[208:211], v[82:85]
	v_mfma_i32_16x16x64_i8 v[82:85], v[188:191], v[224:227], v[82:85]
	v_mfma_i32_16x16x64_i8 v[66:69], v[184:187], v[228:231], v[66:69]
	v_mfma_i32_16x16x64_i8 v[66:69], v[188:191], v[232:235], v[66:69]
	s_setprio 0
	s_barrier
	s_add_i32 s42, s57, s33
	v_lshl_add_u64 v[156:157], v[156:157], 0, s[30:31]
	s_mov_b32 m0, s42
	ds_read_b128 v[192:195], v174 offset:49152
	ds_read_b128 v[196:199], v174 offset:50176
	ds_read_b128 v[200:203], v174 offset:51200
	ds_read_b128 v[204:207], v174 offset:52224
	ds_read_b128 v[208:211], v174 offset:53248
	ds_read_b128 v[224:227], v174 offset:54272
	ds_read_b128 v[228:231], v174 offset:55296
	ds_read_b128 v[232:235], v174 offset:56320
	global_load_lds_dwordx4 v[156:157], off
	s_add_i32 m0, s42, 0x2000
	s_add_u32 s28, s28, 0x40080
	v_lshl_add_u64 v[156:157], v[162:163], 0, s[30:31]
	s_addc_u32 s29, s29, 0
	s_add_i32 s42, s58, s33
	global_load_lds_dwordx4 v[156:157], off
	s_mov_b32 m0, s42
	s_nop 0
	global_load_lds_dwordx4 v0, s[28:29]
	s_add_i32 m0, s42, 0x2000
	s_nop 0
	global_load_lds_dwordx4 v130, s[28:29]
	v_lshl_add_u64 v[156:157], v[164:165], 0, s[30:31]
	s_mov_b32 m0, s48
	s_nop 0
	global_load_lds_dwordx4 v[156:157], off
	v_lshl_add_u64 v[156:157], v[166:167], 0, s[30:31]
	s_mov_b32 m0, s49
	s_nop 0
	global_load_lds_dwordx4 v[156:157], off
	s_waitcnt vmcnt(8)
	s_waitcnt lgkmcnt(0)
	s_barrier
	s_setprio 1
	s_waitcnt lgkmcnt(0)
	v_mfma_i32_16x16x64_i8 v[62:65], v[140:143], v[192:195], v[62:65]
	v_mfma_i32_16x16x64_i8 v[62:65], v[144:147], v[196:199], v[62:65]
	v_mfma_i32_16x16x64_i8 v[46:49], v[140:143], v[200:203], v[46:49]
	v_mfma_i32_16x16x64_i8 v[46:49], v[144:147], v[204:207], v[46:49]
	v_mfma_i32_16x16x64_i8 v[30:33], v[140:143], v[208:211], v[30:33]
	v_mfma_i32_16x16x64_i8 v[30:33], v[144:147], v[224:227], v[30:33]
	v_mfma_i32_16x16x64_i8 v[14:17], v[140:143], v[228:231], v[14:17]
	v_mfma_i32_16x16x64_i8 v[14:17], v[144:147], v[232:235], v[14:17]
	v_mfma_i32_16x16x64_i8 v[58:61], v[148:151], v[192:195], v[58:61]
	v_mfma_i32_16x16x64_i8 v[58:61], v[152:155], v[196:199], v[58:61]
	v_mfma_i32_16x16x64_i8 v[42:45], v[148:151], v[200:203], v[42:45]
	v_mfma_i32_16x16x64_i8 v[42:45], v[152:155], v[204:207], v[42:45]
	v_mfma_i32_16x16x64_i8 v[26:29], v[148:151], v[208:211], v[26:29]
	v_mfma_i32_16x16x64_i8 v[26:29], v[152:155], v[224:227], v[26:29]
	v_mfma_i32_16x16x64_i8 v[10:13], v[148:151], v[228:231], v[10:13]
	v_mfma_i32_16x16x64_i8 v[10:13], v[152:155], v[232:235], v[10:13]
	v_mfma_i32_16x16x64_i8 v[54:57], v[176:179], v[192:195], v[54:57]
	v_mfma_i32_16x16x64_i8 v[54:57], v[180:183], v[196:199], v[54:57]
	v_mfma_i32_16x16x64_i8 v[38:41], v[176:179], v[200:203], v[38:41]
	v_mfma_i32_16x16x64_i8 v[38:41], v[180:183], v[204:207], v[38:41]
	v_mfma_i32_16x16x64_i8 v[22:25], v[176:179], v[208:211], v[22:25]
	v_mfma_i32_16x16x64_i8 v[22:25], v[180:183], v[224:227], v[22:25]
	v_mfma_i32_16x16x64_i8 v[6:9], v[176:179], v[228:231], v[6:9]
	v_mfma_i32_16x16x64_i8 v[6:9], v[180:183], v[232:235], v[6:9]
	v_mfma_i32_16x16x64_i8 v[50:53], v[184:187], v[192:195], v[50:53]
	v_mfma_i32_16x16x64_i8 v[50:53], v[188:191], v[196:199], v[50:53]
	v_mfma_i32_16x16x64_i8 v[34:37], v[184:187], v[200:203], v[34:37]
	v_mfma_i32_16x16x64_i8 v[34:37], v[188:191], v[204:207], v[34:37]
	v_mfma_i32_16x16x64_i8 v[18:21], v[184:187], v[208:211], v[18:21]
	v_mfma_i32_16x16x64_i8 v[18:21], v[188:191], v[224:227], v[18:21]
	v_mfma_i32_16x16x64_i8 v[2:5], v[184:187], v[228:231], v[2:5]
	v_mfma_i32_16x16x64_i8 v[2:5], v[188:191], v[232:235], v[2:5]
	s_setprio 0
	s_barrier
	s_add_i32 s56, s56, 2
	s_add_u32 s26, s26, 0x100
	s_addc_u32 s27, s27, 0
	s_add_u32 s54, s54, 0x100
	s_addc_u32 s55, s55, 0
	s_cmp_gt_u32 s56, 13
	s_cbranch_scc0 .LBB0_641
	v_readlane_b32 s26, v253, 2
	v_readlane_b32 s27, v253, 3
	s_and_b64 vcc, exec, s[26:27]
	s_cbranch_vccz .LBB0_644
	s_barrier

.LBB0_665:
	s_add_u32 s16, s6, 0xfff80080
	s_addc_u32 s17, s7, -1
	s_add_i32 s57, 0, 0x10000
	s_cmp_eq_u32 s56, 28
	s_cselect_b32 s21, s9, s17
	s_cselect_b32 s20, s18, s16
	s_cselect_b32 s17, s5, s55
	s_cselect_b32 s16, s19, s54
	s_add_i32 s60, 0, 0x14000
	v_add_u32_e32 v142, s57, v193
	v_add_u32_e32 v162, s60, v193
	ds_read_b128 v[130:133], v142
	ds_read_b128 v[134:137], v142 offset:1024
	ds_read_b128 v[138:141], v142 offset:2048
	ds_read_b128 v[142:145], v142 offset:3072
	ds_read_b128 v[158:161], v162
	ds_read_b128 v[174:177], v162 offset:1024
	ds_read_b128 v[178:181], v162 offset:2048
	ds_read_b128 v[182:185], v162 offset:3072
	s_add_i32 m0, s26, 0xc000
	ds_read_b128 v[186:189], v196
	ds_read_b128 v[198:201], v196 offset:1024
	ds_read_b128 v[202:205], v196 offset:2048
	ds_read_b128 v[206:209], v196 offset:3072
	ds_read_b128 v[224:227], v196 offset:4096
	ds_read_b128 v[228:231], v196 offset:5120
	ds_read_b128 v[232:235], v196 offset:6144
	ds_read_b128 v[236:239], v196 offset:7168
	global_load_lds_dwordx4 v154, s[6:7]
	s_add_i32 m0, s26, 0xe000
	s_nop 0
	global_load_lds_dwordx4 v156, s[6:7]
	s_waitcnt vmcnt(8)
	s_waitcnt lgkmcnt(0)
	s_barrier
	s_setprio 1
	s_waitcnt lgkmcnt(0)
	v_mfma_f32_16x16x32_bf16 v[126:129], v[130:133], v[186:189], v[126:129]
	v_mfma_f32_16x16x32_bf16 v[126:129], v[134:137], v[198:201], v[126:129]
	v_mfma_f32_16x16x32_bf16 v[110:113], v[130:133], v[202:205], v[110:113]
	v_mfma_f32_16x16x32_bf16 v[110:113], v[134:137], v[206:209], v[110:113]
	v_mfma_f32_16x16x32_bf16 v[94:97], v[130:133], v[224:227], v[94:97]
	v_mfma_f32_16x16x32_bf16 v[94:97], v[134:137], v[228:231], v[94:97]
	v_mfma_f32_16x16x32_bf16 v[78:81], v[130:133], v[232:235], v[78:81]
	v_mfma_f32_16x16x32_bf16 v[78:81], v[134:137], v[236:239], v[78:81]
	v_mfma_f32_16x16x32_bf16 v[122:125], v[138:141], v[186:189], v[122:125]
	v_mfma_f32_16x16x32_bf16 v[122:125], v[142:145], v[198:201], v[122:125]
	v_mfma_f32_16x16x32_bf16 v[106:109], v[138:141], v[202:205], v[106:109]
	v_mfma_f32_16x16x32_bf16 v[106:109], v[142:145], v[206:209], v[106:109]
	v_mfma_f32_16x16x32_bf16 v[90:93], v[138:141], v[224:227], v[90:93]
	v_mfma_f32_16x16x32_bf16 v[90:93], v[142:145], v[228:231], v[90:93]
	v_mfma_f32_16x16x32_bf16 v[74:77], v[138:141], v[232:235], v[74:77]
	v_mfma_f32_16x16x32_bf16 v[74:77], v[142:145], v[236:239], v[74:77]
	v_mfma_f32_16x16x32_bf16 v[118:121], v[158:161], v[186:189], v[118:121]
	v_mfma_f32_16x16x32_bf16 v[118:121], v[174:177], v[198:201], v[118:121]
	v_mfma_f32_16x16x32_bf16 v[102:105], v[158:161], v[202:205], v[102:105]
	v_mfma_f32_16x16x32_bf16 v[102:105], v[174:177], v[206:209], v[102:105]
	v_mfma_f32_16x16x32_bf16 v[86:89], v[158:161], v[224:227], v[86:89]
	v_mfma_f32_16x16x32_bf16 v[86:89], v[174:177], v[228:231], v[86:89]
	v_mfma_f32_16x16x32_bf16 v[70:73], v[158:161], v[232:235], v[70:73]
	v_mfma_f32_16x16x32_bf16 v[70:73], v[174:177], v[236:239], v[70:73]
	v_mfma_f32_16x16x32_bf16 v[114:117], v[178:181], v[186:189], v[114:117]
	v_mfma_f32_16x16x32_bf16 v[114:117], v[182:185], v[198:201], v[114:117]
	v_mfma_f32_16x16x32_bf16 v[98:101], v[178:181], v[202:205], v[98:101]
	v_mfma_f32_16x16x32_bf16 v[98:101], v[182:185], v[206:209], v[98:101]
	v_mfma_f32_16x16x32_bf16 v[82:85], v[178:181], v[224:227], v[82:85]
	v_mfma_f32_16x16x32_bf16 v[82:85], v[182:185], v[228:231], v[82:85]
	v_mfma_f32_16x16x32_bf16 v[66:69], v[178:181], v[232:235], v[66:69]
	v_mfma_f32_16x16x32_bf16 v[66:69], v[182:185], v[236:239], v[66:69]
	s_setprio 0
	s_barrier
	s_add_i32 s57, s57, s33
	v_lshl_add_u64 v[162:163], s[16:17], 0, v[0:1]
	s_mov_b32 m0, s57
	ds_read_b128 v[186:189], v196 offset:16384
	ds_read_b128 v[198:201], v196 offset:17408
	ds_read_b128 v[202:205], v196 offset:18432
	ds_read_b128 v[206:209], v196 offset:19456
	ds_read_b128 v[224:227], v196 offset:20480
	ds_read_b128 v[228:231], v196 offset:21504
	ds_read_b128 v[232:235], v196 offset:22528
	ds_read_b128 v[236:239], v196 offset:23552
	global_load_lds_dwordx4 v[162:163], off
	s_add_i32 m0, s57, 0x2000
	s_add_u32 s58, s16, 0x80000
	v_lshl_add_u64 v[164:165], s[16:17], 0, v[146:147]
	s_addc_u32 s59, s17, 0
	s_add_i32 s57, s60, s33
	global_load_lds_dwordx4 v[164:165], off
	s_mov_b32 m0, s57
	v_lshl_add_u64 v[168:169], s[20:21], 0, v[148:149]
	global_load_lds_dwordx4 v0, s[58:59]
	s_add_i32 m0, s57, 0x2000
	s_nop 0
	global_load_lds_dwordx4 v146, s[58:59]
	v_lshl_add_u64 v[166:167], s[20:21], 0, v[150:151]
	s_mov_b32 m0, s26
	s_nop 0
	global_load_lds_dwordx4 v[166:167], off
	s_mov_b32 m0, s27
	s_nop 0
	global_load_lds_dwordx4 v[168:169], off
	s_waitcnt vmcnt(8)
	s_waitcnt lgkmcnt(0)
	s_barrier
	s_setprio 1
	s_waitcnt lgkmcnt(0)
	v_mfma_f32_16x16x32_bf16 v[62:65], v[130:133], v[186:189], v[62:65]
	v_mfma_f32_16x16x32_bf16 v[62:65], v[134:137], v[198:201], v[62:65]
	v_mfma_f32_16x16x32_bf16 v[46:49], v[130:133], v[202:205], v[46:49]
	v_mfma_f32_16x16x32_bf16 v[46:49], v[134:137], v[206:209], v[46:49]
	v_mfma_f32_16x16x32_bf16 v[30:33], v[130:133], v[224:227], v[30:33]
	v_mfma_f32_16x16x32_bf16 v[30:33], v[134:137], v[228:231], v[30:33]
	v_mfma_f32_16x16x32_bf16 v[14:17], v[130:133], v[232:235], v[14:17]
	v_mfma_f32_16x16x32_bf16 v[14:17], v[134:137], v[236:239], v[14:17]
	v_mfma_f32_16x16x32_bf16 v[58:61], v[138:141], v[186:189], v[58:61]
	v_mfma_f32_16x16x32_bf16 v[58:61], v[142:145], v[198:201], v[58:61]
	v_mfma_f32_16x16x32_bf16 v[42:45], v[138:141], v[202:205], v[42:45]
	v_mfma_f32_16x16x32_bf16 v[42:45], v[142:145], v[206:209], v[42:45]
	v_mfma_f32_16x16x32_bf16 v[26:29], v[138:141], v[224:227], v[26:29]
	v_mfma_f32_16x16x32_bf16 v[26:29], v[142:145], v[228:231], v[26:29]
	v_mfma_f32_16x16x32_bf16 v[10:13], v[138:141], v[232:235], v[10:13]
	v_mfma_f32_16x16x32_bf16 v[10:13], v[142:145], v[236:239], v[10:13]
	v_mfma_f32_16x16x32_bf16 v[54:57], v[158:161], v[186:189], v[54:57]
	v_mfma_f32_16x16x32_bf16 v[54:57], v[174:177], v[198:201], v[54:57]
	v_mfma_f32_16x16x32_bf16 v[38:41], v[158:161], v[202:205], v[38:41]
	v_mfma_f32_16x16x32_bf16 v[38:41], v[174:177], v[206:209], v[38:41]
	v_mfma_f32_16x16x32_bf16 v[22:25], v[158:161], v[224:227], v[22:25]
	v_mfma_f32_16x16x32_bf16 v[22:25], v[174:177], v[228:231], v[22:25]
	v_mfma_f32_16x16x32_bf16 v[6:9], v[158:161], v[232:235], v[6:9]
	v_mfma_f32_16x16x32_bf16 v[6:9], v[174:177], v[236:239], v[6:9]
	v_mfma_f32_16x16x32_bf16 v[50:53], v[178:181], v[186:189], v[50:53]
	v_mfma_f32_16x16x32_bf16 v[50:53], v[182:185], v[198:201], v[50:53]
	v_mfma_f32_16x16x32_bf16 v[34:37], v[178:181], v[202:205], v[34:37]
	v_mfma_f32_16x16x32_bf16 v[34:37], v[182:185], v[206:209], v[34:37]
	v_mfma_f32_16x16x32_bf16 v[18:21], v[178:181], v[224:227], v[18:21]
	v_mfma_f32_16x16x32_bf16 v[18:21], v[182:185], v[228:231], v[18:21]
	v_mfma_f32_16x16x32_bf16 v[2:5], v[178:181], v[232:235], v[2:5]
	v_mfma_f32_16x16x32_bf16 v[2:5], v[182:185], v[236:239], v[2:5]
	s_setprio 0
	s_barrier
	s_add_i32 s57, 0, 0x18000
	s_add_i32 s58, 0, 0x1c000
	v_add_u32_e32 v142, s57, v193
	v_add_u32_e32 v170, s58, v193
	ds_read_b128 v[130:133], v142
	ds_read_b128 v[134:137], v142 offset:1024
	ds_read_b128 v[138:141], v142 offset:2048
	ds_read_b128 v[142:145], v142 offset:3072
	ds_read_b128 v[158:161], v170
	ds_read_b128 v[174:177], v170 offset:1024
	ds_read_b128 v[178:181], v170 offset:2048
	ds_read_b128 v[182:185], v170 offset:3072
	s_add_u32 s20, s20, 0x80000
	s_addc_u32 s21, s21, 0
	s_mov_b32 m0, s28
	ds_read_b128 v[186:189], v196 offset:32768
	ds_read_b128 v[198:201], v196 offset:33792
	ds_read_b128 v[202:205], v196 offset:34816
	ds_read_b128 v[206:209], v196 offset:35840
	ds_read_b128 v[224:227], v196 offset:36864
	ds_read_b128 v[228:231], v196 offset:37888
	ds_read_b128 v[232:235], v196 offset:38912
	ds_read_b128 v[236:239], v196 offset:39936
	global_load_lds_dwordx4 v150, s[20:21]
	s_mov_b32 m0, s29
	s_nop 0
	global_load_lds_dwordx4 v148, s[20:21]
	s_waitcnt vmcnt(8)
	s_waitcnt lgkmcnt(0)
	s_barrier
	s_setprio 1
	s_waitcnt lgkmcnt(0)
	v_mfma_f32_16x16x32_bf16 v[126:129], v[130:133], v[186:189], v[126:129]
	v_mfma_f32_16x16x32_bf16 v[126:129], v[134:137], v[198:201], v[126:129]
	v_mfma_f32_16x16x32_bf16 v[110:113], v[130:133], v[202:205], v[110:113]
	v_mfma_f32_16x16x32_bf16 v[110:113], v[134:137], v[206:209], v[110:113]
	v_mfma_f32_16x16x32_bf16 v[94:97], v[130:133], v[224:227], v[94:97]
	v_mfma_f32_16x16x32_bf16 v[94:97], v[134:137], v[228:231], v[94:97]
	v_mfma_f32_16x16x32_bf16 v[78:81], v[130:133], v[232:235], v[78:81]
	v_mfma_f32_16x16x32_bf16 v[78:81], v[134:137], v[236:239], v[78:81]
	v_mfma_f32_16x16x32_bf16 v[122:125], v[138:141], v[186:189], v[122:125]
	v_mfma_f32_16x16x32_bf16 v[122:125], v[142:145], v[198:201], v[122:125]
	v_mfma_f32_16x16x32_bf16 v[106:109], v[138:141], v[202:205], v[106:109]
	v_mfma_f32_16x16x32_bf16 v[106:109], v[142:145], v[206:209], v[106:109]
	v_mfma_f32_16x16x32_bf16 v[90:93], v[138:141], v[224:227], v[90:93]
	v_mfma_f32_16x16x32_bf16 v[90:93], v[142:145], v[228:231], v[90:93]
	v_mfma_f32_16x16x32_bf16 v[74:77], v[138:141], v[232:235], v[74:77]
	v_mfma_f32_16x16x32_bf16 v[74:77], v[142:145], v[236:239], v[74:77]
	v_mfma_f32_16x16x32_bf16 v[118:121], v[158:161], v[186:189], v[118:121]
	v_mfma_f32_16x16x32_bf16 v[118:121], v[174:177], v[198:201], v[118:121]
	v_mfma_f32_16x16x32_bf16 v[102:105], v[158:161], v[202:205], v[102:105]
	v_mfma_f32_16x16x32_bf16 v[102:105], v[174:177], v[206:209], v[102:105]
	v_mfma_f32_16x16x32_bf16 v[86:89], v[158:161], v[224:227], v[86:89]
	v_mfma_f32_16x16x32_bf16 v[86:89], v[174:177], v[228:231], v[86:89]
	v_mfma_f32_16x16x32_bf16 v[70:73], v[158:161], v[232:235], v[70:73]
	v_mfma_f32_16x16x32_bf16 v[70:73], v[174:177], v[236:239], v[70:73]
	v_mfma_f32_16x16x32_bf16 v[114:117], v[178:181], v[186:189], v[114:117]
	v_mfma_f32_16x16x32_bf16 v[114:117], v[182:185], v[198:201], v[114:117]
	v_mfma_f32_16x16x32_bf16 v[98:101], v[178:181], v[202:205], v[98:101]
	v_mfma_f32_16x16x32_bf16 v[98:101], v[182:185], v[206:209], v[98:101]
	v_mfma_f32_16x16x32_bf16 v[82:85], v[178:181], v[224:227], v[82:85]
	v_mfma_f32_16x16x32_bf16 v[82:85], v[182:185], v[228:231], v[82:85]
	v_mfma_f32_16x16x32_bf16 v[66:69], v[178:181], v[232:235], v[66:69]
	v_mfma_f32_16x16x32_bf16 v[66:69], v[182:185], v[236:239], v[66:69]
	s_setprio 0
	s_barrier
	s_add_i32 s20, s57, s33
	v_lshl_add_u64 v[162:163], v[162:163], 0, s[30:31]
	s_mov_b32 m0, s20
	ds_read_b128 v[186:189], v196 offset:49152
	ds_read_b128 v[198:201], v196 offset:50176
	ds_read_b128 v[202:205], v196 offset:51200
	ds_read_b128 v[206:209], v196 offset:52224
	ds_read_b128 v[224:227], v196 offset:53248
	ds_read_b128 v[228:231], v196 offset:54272
	ds_read_b128 v[232:235], v196 offset:55296
	ds_read_b128 v[236:239], v196 offset:56320
	global_load_lds_dwordx4 v[162:163], off
	s_add_i32 m0, s20, 0x2000
	s_add_u32 s16, s16, 0x80080
	v_lshl_add_u64 v[162:163], v[164:165], 0, s[30:31]
	s_addc_u32 s17, s17, 0
	s_add_i32 s20, s58, s33
	global_load_lds_dwordx4 v[162:163], off
	s_mov_b32 m0, s20
	s_nop 0
	global_load_lds_dwordx4 v0, s[16:17]
	s_add_i32 m0, s20, 0x2000
	s_nop 0
	global_load_lds_dwordx4 v146, s[16:17]
	v_lshl_add_u64 v[162:163], v[166:167], 0, s[30:31]
	s_mov_b32 m0, s48
	s_nop 0
	global_load_lds_dwordx4 v[162:163], off
	v_lshl_add_u64 v[162:163], v[168:169], 0, s[30:31]
	s_mov_b32 m0, s49
	s_nop 0
	global_load_lds_dwordx4 v[162:163], off
	s_waitcnt vmcnt(8)
	s_waitcnt lgkmcnt(0)
	s_barrier
	s_setprio 1
	s_waitcnt lgkmcnt(0)
	v_mfma_f32_16x16x32_bf16 v[62:65], v[130:133], v[186:189], v[62:65]
	v_mfma_f32_16x16x32_bf16 v[62:65], v[134:137], v[198:201], v[62:65]
	v_mfma_f32_16x16x32_bf16 v[46:49], v[130:133], v[202:205], v[46:49]
	v_mfma_f32_16x16x32_bf16 v[46:49], v[134:137], v[206:209], v[46:49]
	v_mfma_f32_16x16x32_bf16 v[30:33], v[130:133], v[224:227], v[30:33]
	v_mfma_f32_16x16x32_bf16 v[30:33], v[134:137], v[228:231], v[30:33]
	v_mfma_f32_16x16x32_bf16 v[14:17], v[130:133], v[232:235], v[14:17]
	v_mfma_f32_16x16x32_bf16 v[14:17], v[134:137], v[236:239], v[14:17]
	v_mfma_f32_16x16x32_bf16 v[58:61], v[138:141], v[186:189], v[58:61]
	v_mfma_f32_16x16x32_bf16 v[58:61], v[142:145], v[198:201], v[58:61]
	v_mfma_f32_16x16x32_bf16 v[42:45], v[138:141], v[202:205], v[42:45]
	v_mfma_f32_16x16x32_bf16 v[42:45], v[142:145], v[206:209], v[42:45]
	v_mfma_f32_16x16x32_bf16 v[26:29], v[138:141], v[224:227], v[26:29]
	v_mfma_f32_16x16x32_bf16 v[26:29], v[142:145], v[228:231], v[26:29]
	v_mfma_f32_16x16x32_bf16 v[10:13], v[138:141], v[232:235], v[10:13]
	v_mfma_f32_16x16x32_bf16 v[10:13], v[142:145], v[236:239], v[10:13]
	v_mfma_f32_16x16x32_bf16 v[54:57], v[158:161], v[186:189], v[54:57]
	v_mfma_f32_16x16x32_bf16 v[54:57], v[174:177], v[198:201], v[54:57]
	v_mfma_f32_16x16x32_bf16 v[38:41], v[158:161], v[202:205], v[38:41]
	v_mfma_f32_16x16x32_bf16 v[38:41], v[174:177], v[206:209], v[38:41]
	v_mfma_f32_16x16x32_bf16 v[22:25], v[158:161], v[224:227], v[22:25]
	v_mfma_f32_16x16x32_bf16 v[22:25], v[174:177], v[228:231], v[22:25]
	v_mfma_f32_16x16x32_bf16 v[6:9], v[158:161], v[232:235], v[6:9]
	v_mfma_f32_16x16x32_bf16 v[6:9], v[174:177], v[236:239], v[6:9]
	v_mfma_f32_16x16x32_bf16 v[50:53], v[178:181], v[186:189], v[50:53]
	v_mfma_f32_16x16x32_bf16 v[50:53], v[182:185], v[198:201], v[50:53]
	v_mfma_f32_16x16x32_bf16 v[34:37], v[178:181], v[202:205], v[34:37]
	v_mfma_f32_16x16x32_bf16 v[34:37], v[182:185], v[206:209], v[34:37]
	v_mfma_f32_16x16x32_bf16 v[18:21], v[178:181], v[224:227], v[18:21]
	v_mfma_f32_16x16x32_bf16 v[18:21], v[182:185], v[228:231], v[18:21]
	v_mfma_f32_16x16x32_bf16 v[2:5], v[178:181], v[232:235], v[2:5]
	v_mfma_f32_16x16x32_bf16 v[2:5], v[182:185], v[236:239], v[2:5]
	s_setprio 0
	s_barrier
	s_add_i32 s56, s56, 2
	s_add_u32 s6, s6, 0x100
	s_addc_u32 s7, s7, 0
	s_add_u32 s54, s54, 0x100
	s_addc_u32 s55, s55, 0
	s_cmp_gt_u32 s56, 29
	s_cbranch_scc0 .LBB0_665
	v_readlane_b32 s6, v253, 2
	v_readlane_b32 s7, v253, 3
	s_and_b64 vcc, exec, s[6:7]
	s_cbranch_vccz .LBB0_670
	s_barrier
	s_cmp_lt_i32 s51, 22
	s_mov_b64 s[6:7], -1
	s_cbranch_scc1 .LBB0_671

.LBB0_1913:
	s_add_i32 s52, s20, 2
	s_add_u32 s14, s16, 0xfff80080
	s_addc_u32 s15, s17, -1
	s_add_i32 s53, 0, 0x10000
	s_cmp_eq_u32 s49, s20
	s_cselect_b32 s21, s7, s15
	s_cselect_b32 s20, s6, s14
	v_add_u32_e32 v0, s53, v189
	s_cselect_b32 s15, s13, s51
	s_cselect_b32 s14, s12, s50
	s_add_i32 s56, 0, 0x14000
	ds_read_b128 v[132:135], v0
	ds_read_b128 v[148:151], v0 offset:1024
	ds_read_b128 v[152:155], v0 offset:2048
	ds_read_b128 v[156:159], v0 offset:3072
	v_add_u32_e32 v0, s56, v189
	ds_read_b128 v[160:163], v0
	ds_read_b128 v[164:167], v0 offset:1024
	ds_read_b128 v[168:171], v0 offset:2048
	ds_read_b128 v[172:175], v0 offset:3072
	s_add_i32 m0, s26, 0xc000
	ds_read_b128 v[176:179], v191
	ds_read_b128 v[180:183], v191 offset:1024
	ds_read_b128 v[184:187], v191 offset:2048
	ds_read_b128 v[192:195], v191 offset:3072
	ds_read_b128 v[196:199], v191 offset:4096
	ds_read_b128 v[200:203], v191 offset:5120
	ds_read_b128 v[204:207], v191 offset:6144
	ds_read_b128 v[208:211], v191 offset:7168
	global_load_lds_dwordx4 v144, s[16:17]
	s_add_i32 m0, s26, 0xe000
	s_nop 0
	global_load_lds_dwordx4 v146, s[16:17]
	s_waitcnt vmcnt(8)
	s_waitcnt lgkmcnt(0)
	s_barrier
	s_setprio 1
	s_waitcnt lgkmcnt(0)
	v_mfma_f32_16x16x32_bf16 v[128:131], v[132:135], v[176:179], v[128:131]
	v_mfma_f32_16x16x32_bf16 v[128:131], v[148:151], v[180:183], v[128:131]
	v_mfma_f32_16x16x32_bf16 v[120:123], v[132:135], v[184:187], v[120:123]
	v_mfma_f32_16x16x32_bf16 v[120:123], v[148:151], v[192:195], v[120:123]
	v_mfma_f32_16x16x32_bf16 v[112:115], v[132:135], v[196:199], v[112:115]
	v_mfma_f32_16x16x32_bf16 v[112:115], v[148:151], v[200:203], v[112:115]
	v_mfma_f32_16x16x32_bf16 v[104:107], v[132:135], v[204:207], v[104:107]
	v_mfma_f32_16x16x32_bf16 v[104:107], v[148:151], v[208:211], v[104:107]
	v_mfma_f32_16x16x32_bf16 v[124:127], v[152:155], v[176:179], v[124:127]
	v_mfma_f32_16x16x32_bf16 v[124:127], v[156:159], v[180:183], v[124:127]
	v_mfma_f32_16x16x32_bf16 v[116:119], v[152:155], v[184:187], v[116:119]
	v_mfma_f32_16x16x32_bf16 v[116:119], v[156:159], v[192:195], v[116:119]
	v_mfma_f32_16x16x32_bf16 v[108:111], v[152:155], v[196:199], v[108:111]
	v_mfma_f32_16x16x32_bf16 v[108:111], v[156:159], v[200:203], v[108:111]
	v_mfma_f32_16x16x32_bf16 v[100:103], v[152:155], v[204:207], v[100:103]
	v_mfma_f32_16x16x32_bf16 v[100:103], v[156:159], v[208:211], v[100:103]
	v_mfma_f32_16x16x32_bf16 v[96:99], v[160:163], v[176:179], v[96:99]
	v_mfma_f32_16x16x32_bf16 v[96:99], v[164:167], v[180:183], v[96:99]
	v_mfma_f32_16x16x32_bf16 v[88:91], v[160:163], v[184:187], v[88:91]
	v_mfma_f32_16x16x32_bf16 v[88:91], v[164:167], v[192:195], v[88:91]
	v_mfma_f32_16x16x32_bf16 v[80:83], v[160:163], v[196:199], v[80:83]
	v_mfma_f32_16x16x32_bf16 v[80:83], v[164:167], v[200:203], v[80:83]
	v_mfma_f32_16x16x32_bf16 v[72:75], v[160:163], v[204:207], v[72:75]
	v_mfma_f32_16x16x32_bf16 v[72:75], v[164:167], v[208:211], v[72:75]
	v_mfma_f32_16x16x32_bf16 v[92:95], v[168:171], v[176:179], v[92:95]
	v_mfma_f32_16x16x32_bf16 v[92:95], v[172:175], v[180:183], v[92:95]
	v_mfma_f32_16x16x32_bf16 v[84:87], v[168:171], v[184:187], v[84:87]
	v_mfma_f32_16x16x32_bf16 v[84:87], v[172:175], v[192:195], v[84:87]
	v_mfma_f32_16x16x32_bf16 v[76:79], v[168:171], v[196:199], v[76:79]
	v_mfma_f32_16x16x32_bf16 v[76:79], v[172:175], v[200:203], v[76:79]
	v_mfma_f32_16x16x32_bf16 v[68:71], v[168:171], v[204:207], v[68:71]
	v_mfma_f32_16x16x32_bf16 v[68:71], v[172:175], v[208:211], v[68:71]
	s_setprio 0
	s_barrier
	s_add_i32 s53, s53, s33
	v_lshl_add_u64 v[212:213], s[14:15], 0, v[140:141]
	s_mov_b32 m0, s53
	ds_read_b128 v[176:179], v191 offset:16384
	ds_read_b128 v[180:183], v191 offset:17408
	ds_read_b128 v[184:187], v191 offset:18432
	ds_read_b128 v[192:195], v191 offset:19456
	ds_read_b128 v[196:199], v191 offset:20480
	ds_read_b128 v[200:203], v191 offset:21504
	ds_read_b128 v[204:207], v191 offset:22528
	ds_read_b128 v[208:211], v191 offset:23552
	global_load_lds_dwordx4 v[212:213], off
	s_add_i32 m0, s53, 0x2000
	s_add_u32 s54, s14, 0x80000
	v_lshl_add_u64 v[220:221], s[14:15], 0, v[136:137]
	s_addc_u32 s55, s15, 0
	s_add_i32 s53, s56, s33
	global_load_lds_dwordx4 v[220:221], off
	s_mov_b32 m0, s53
	v_lshl_add_u64 v[224:225], s[20:21], 0, v[142:143]
	global_load_lds_dwordx4 v140, s[54:55]
	s_add_i32 m0, s53, 0x2000
	v_lshl_add_u64 v[226:227], s[20:21], 0, v[138:139]
	global_load_lds_dwordx4 v136, s[54:55]
	s_mov_b32 m0, s26
	s_nop 0
	global_load_lds_dwordx4 v[224:225], off
	s_mov_b32 m0, s27
	s_nop 0
	global_load_lds_dwordx4 v[226:227], off
	s_waitcnt vmcnt(8)
	s_waitcnt lgkmcnt(0)
	s_barrier
	s_setprio 1
	s_waitcnt lgkmcnt(0)
	v_mfma_f32_16x16x32_bf16 v[64:67], v[132:135], v[176:179], v[64:67]
	v_mfma_f32_16x16x32_bf16 v[64:67], v[148:151], v[180:183], v[64:67]
	v_mfma_f32_16x16x32_bf16 v[56:59], v[132:135], v[184:187], v[56:59]
	v_mfma_f32_16x16x32_bf16 v[56:59], v[148:151], v[192:195], v[56:59]
	v_mfma_f32_16x16x32_bf16 v[48:51], v[132:135], v[196:199], v[48:51]
	v_mfma_f32_16x16x32_bf16 v[48:51], v[148:151], v[200:203], v[48:51]
	v_mfma_f32_16x16x32_bf16 v[40:43], v[132:135], v[204:207], v[40:43]
	v_mfma_f32_16x16x32_bf16 v[40:43], v[148:151], v[208:211], v[40:43]
	v_mfma_f32_16x16x32_bf16 v[60:63], v[152:155], v[176:179], v[60:63]
	v_mfma_f32_16x16x32_bf16 v[60:63], v[156:159], v[180:183], v[60:63]
	v_mfma_f32_16x16x32_bf16 v[52:55], v[152:155], v[184:187], v[52:55]
	v_mfma_f32_16x16x32_bf16 v[52:55], v[156:159], v[192:195], v[52:55]
	v_mfma_f32_16x16x32_bf16 v[44:47], v[152:155], v[196:199], v[44:47]
	v_mfma_f32_16x16x32_bf16 v[44:47], v[156:159], v[200:203], v[44:47]
	v_mfma_f32_16x16x32_bf16 v[36:39], v[152:155], v[204:207], v[36:39]
	v_mfma_f32_16x16x32_bf16 v[36:39], v[156:159], v[208:211], v[36:39]
	v_mfma_f32_16x16x32_bf16 v[32:35], v[160:163], v[176:179], v[32:35]
	v_mfma_f32_16x16x32_bf16 v[32:35], v[164:167], v[180:183], v[32:35]
	v_mfma_f32_16x16x32_bf16 v[24:27], v[160:163], v[184:187], v[24:27]
	v_mfma_f32_16x16x32_bf16 v[24:27], v[164:167], v[192:195], v[24:27]
	v_mfma_f32_16x16x32_bf16 v[16:19], v[160:163], v[196:199], v[16:19]
	v_mfma_f32_16x16x32_bf16 v[16:19], v[164:167], v[200:203], v[16:19]
	v_mfma_f32_16x16x32_bf16 v[8:11], v[160:163], v[204:207], v[8:11]
	v_mfma_f32_16x16x32_bf16 v[8:11], v[164:167], v[208:211], v[8:11]
	v_mfma_f32_16x16x32_bf16 v[28:31], v[168:171], v[176:179], v[28:31]
	v_mfma_f32_16x16x32_bf16 v[28:31], v[172:175], v[180:183], v[28:31]
	v_mfma_f32_16x16x32_bf16 v[20:23], v[168:171], v[184:187], v[20:23]
	v_mfma_f32_16x16x32_bf16 v[20:23], v[172:175], v[192:195], v[20:23]
	v_mfma_f32_16x16x32_bf16 v[12:15], v[168:171], v[196:199], v[12:15]
	v_mfma_f32_16x16x32_bf16 v[12:15], v[172:175], v[200:203], v[12:15]
	v_mfma_f32_16x16x32_bf16 v[2:5], v[168:171], v[204:207], v[4:7]
	v_mfma_f32_16x16x32_bf16 v[2:5], v[172:175], v[208:211], v[2:5]
	s_setprio 0
	s_barrier
	s_add_i32 s53, 0, 0x18000
	v_add_u32_e32 v0, s53, v189
	s_add_i32 s54, 0, 0x1c000
	ds_read_b128 v[132:135], v0
	ds_read_b128 v[148:151], v0 offset:1024
	ds_read_b128 v[152:155], v0 offset:2048
	ds_read_b128 v[156:159], v0 offset:3072
	v_add_u32_e32 v0, s54, v189
	ds_read_b128 v[160:163], v0
	ds_read_b128 v[164:167], v0 offset:1024
	ds_read_b128 v[168:171], v0 offset:2048
	ds_read_b128 v[172:175], v0 offset:3072
	s_add_u32 s20, s20, 0x80000
	s_addc_u32 s21, s21, 0
	s_mov_b32 m0, s28
	ds_read_b128 v[176:179], v191 offset:32768
	ds_read_b128 v[180:183], v191 offset:33792
	ds_read_b128 v[184:187], v191 offset:34816
	ds_read_b128 v[192:195], v191 offset:35840
	ds_read_b128 v[196:199], v191 offset:36864
	ds_read_b128 v[200:203], v191 offset:37888
	ds_read_b128 v[204:207], v191 offset:38912
	ds_read_b128 v[208:211], v191 offset:39936
	global_load_lds_dwordx4 v142, s[20:21]
	s_mov_b32 m0, s29
	s_nop 0
	global_load_lds_dwordx4 v138, s[20:21]
	s_waitcnt vmcnt(8)
	s_waitcnt lgkmcnt(0)
	s_barrier
	s_setprio 1
	s_waitcnt lgkmcnt(0)
	v_mfma_f32_16x16x32_bf16 v[128:131], v[132:135], v[176:179], v[128:131]
	v_mfma_f32_16x16x32_bf16 v[128:131], v[148:151], v[180:183], v[128:131]
	v_mfma_f32_16x16x32_bf16 v[120:123], v[132:135], v[184:187], v[120:123]
	v_mfma_f32_16x16x32_bf16 v[120:123], v[148:151], v[192:195], v[120:123]
	v_mfma_f32_16x16x32_bf16 v[112:115], v[132:135], v[196:199], v[112:115]
	v_mfma_f32_16x16x32_bf16 v[112:115], v[148:151], v[200:203], v[112:115]
	v_mfma_f32_16x16x32_bf16 v[104:107], v[132:135], v[204:207], v[104:107]
	v_mfma_f32_16x16x32_bf16 v[104:107], v[148:151], v[208:211], v[104:107]
	v_mfma_f32_16x16x32_bf16 v[124:127], v[152:155], v[176:179], v[124:127]
	v_mfma_f32_16x16x32_bf16 v[124:127], v[156:159], v[180:183], v[124:127]
	v_mfma_f32_16x16x32_bf16 v[116:119], v[152:155], v[184:187], v[116:119]
	v_mfma_f32_16x16x32_bf16 v[116:119], v[156:159], v[192:195], v[116:119]
	v_mfma_f32_16x16x32_bf16 v[108:111], v[152:155], v[196:199], v[108:111]
	v_mfma_f32_16x16x32_bf16 v[108:111], v[156:159], v[200:203], v[108:111]
	v_mfma_f32_16x16x32_bf16 v[100:103], v[152:155], v[204:207], v[100:103]
	v_mfma_f32_16x16x32_bf16 v[100:103], v[156:159], v[208:211], v[100:103]
	v_mfma_f32_16x16x32_bf16 v[96:99], v[160:163], v[176:179], v[96:99]
	v_mfma_f32_16x16x32_bf16 v[96:99], v[164:167], v[180:183], v[96:99]
	v_mfma_f32_16x16x32_bf16 v[88:91], v[160:163], v[184:187], v[88:91]
	v_mfma_f32_16x16x32_bf16 v[88:91], v[164:167], v[192:195], v[88:91]
	v_mfma_f32_16x16x32_bf16 v[80:83], v[160:163], v[196:199], v[80:83]
	v_mfma_f32_16x16x32_bf16 v[80:83], v[164:167], v[200:203], v[80:83]
	v_mfma_f32_16x16x32_bf16 v[72:75], v[160:163], v[204:207], v[72:75]
	v_mfma_f32_16x16x32_bf16 v[72:75], v[164:167], v[208:211], v[72:75]
	v_mfma_f32_16x16x32_bf16 v[92:95], v[168:171], v[176:179], v[92:95]
	v_mfma_f32_16x16x32_bf16 v[92:95], v[172:175], v[180:183], v[92:95]
	v_mfma_f32_16x16x32_bf16 v[84:87], v[168:171], v[184:187], v[84:87]
	v_mfma_f32_16x16x32_bf16 v[84:87], v[172:175], v[192:195], v[84:87]
	v_mfma_f32_16x16x32_bf16 v[76:79], v[168:171], v[196:199], v[76:79]
	v_mfma_f32_16x16x32_bf16 v[76:79], v[172:175], v[200:203], v[76:79]
	v_mfma_f32_16x16x32_bf16 v[68:71], v[168:171], v[204:207], v[68:71]
	v_mfma_f32_16x16x32_bf16 v[68:71], v[172:175], v[208:211], v[68:71]
	s_setprio 0
	s_barrier
	s_add_i32 s20, s53, s33
	v_lshl_add_u64 v[6:7], v[212:213], 0, s[30:31]
	s_mov_b32 m0, s20
	ds_read_b128 v[176:179], v191 offset:49152
	ds_read_b128 v[180:183], v191 offset:50176
	ds_read_b128 v[184:187], v191 offset:51200
	ds_read_b128 v[192:195], v191 offset:52224
	ds_read_b128 v[196:199], v191 offset:53248
	ds_read_b128 v[200:203], v191 offset:54272
	ds_read_b128 v[204:207], v191 offset:55296
	ds_read_b128 v[208:211], v191 offset:56320
	global_load_lds_dwordx4 v[6:7], off
	s_add_i32 m0, s20, 0x2000
	s_add_u32 s14, s14, 0x80080
	v_lshl_add_u64 v[6:7], v[220:221], 0, s[30:31]
	s_addc_u32 s15, s15, 0
	s_add_i32 s20, s54, s33
	global_load_lds_dwordx4 v[6:7], off
	s_mov_b32 m0, s20
	s_nop 0
	global_load_lds_dwordx4 v140, s[14:15]
	s_add_i32 m0, s20, 0x2000
	s_nop 0
	global_load_lds_dwordx4 v136, s[14:15]
	v_lshl_add_u64 v[6:7], v[224:225], 0, s[30:31]
	s_mov_b32 m0, s34
	s_nop 0
	global_load_lds_dwordx4 v[6:7], off
	v_lshl_add_u64 v[6:7], v[226:227], 0, s[30:31]
	s_mov_b32 m0, s35
	s_nop 0
	global_load_lds_dwordx4 v[6:7], off
	s_waitcnt vmcnt(8)
	s_waitcnt lgkmcnt(0)
	s_barrier
	s_setprio 1
	s_waitcnt lgkmcnt(0)
	v_mfma_f32_16x16x32_bf16 v[64:67], v[132:135], v[176:179], v[64:67]
	v_mfma_f32_16x16x32_bf16 v[64:67], v[148:151], v[180:183], v[64:67]
	v_mfma_f32_16x16x32_bf16 v[56:59], v[132:135], v[184:187], v[56:59]
	v_mfma_f32_16x16x32_bf16 v[56:59], v[148:151], v[192:195], v[56:59]
	v_mfma_f32_16x16x32_bf16 v[48:51], v[132:135], v[196:199], v[48:51]
	v_mfma_f32_16x16x32_bf16 v[48:51], v[148:151], v[200:203], v[48:51]
	v_mfma_f32_16x16x32_bf16 v[40:43], v[132:135], v[204:207], v[40:43]
	v_mfma_f32_16x16x32_bf16 v[40:43], v[148:151], v[208:211], v[40:43]
	v_mfma_f32_16x16x32_bf16 v[60:63], v[152:155], v[176:179], v[60:63]
	v_mfma_f32_16x16x32_bf16 v[60:63], v[156:159], v[180:183], v[60:63]
	v_mfma_f32_16x16x32_bf16 v[52:55], v[152:155], v[184:187], v[52:55]
	v_mfma_f32_16x16x32_bf16 v[52:55], v[156:159], v[192:195], v[52:55]
	v_mfma_f32_16x16x32_bf16 v[44:47], v[152:155], v[196:199], v[44:47]
	v_mfma_f32_16x16x32_bf16 v[44:47], v[156:159], v[200:203], v[44:47]
	v_mfma_f32_16x16x32_bf16 v[36:39], v[152:155], v[204:207], v[36:39]
	v_mfma_f32_16x16x32_bf16 v[36:39], v[156:159], v[208:211], v[36:39]
	v_mfma_f32_16x16x32_bf16 v[32:35], v[160:163], v[176:179], v[32:35]
	v_mfma_f32_16x16x32_bf16 v[32:35], v[164:167], v[180:183], v[32:35]
	v_mfma_f32_16x16x32_bf16 v[24:27], v[160:163], v[184:187], v[24:27]
	v_mfma_f32_16x16x32_bf16 v[24:27], v[164:167], v[192:195], v[24:27]
	v_mfma_f32_16x16x32_bf16 v[16:19], v[160:163], v[196:199], v[16:19]
	v_mfma_f32_16x16x32_bf16 v[16:19], v[164:167], v[200:203], v[16:19]
	v_mfma_f32_16x16x32_bf16 v[6:9], v[160:163], v[204:207], v[8:11]
	v_mfma_f32_16x16x32_bf16 v[28:31], v[168:171], v[176:179], v[28:31]
	v_mfma_f32_16x16x32_bf16 v[28:31], v[172:175], v[180:183], v[28:31]
	v_mfma_f32_16x16x32_bf16 v[20:23], v[168:171], v[184:187], v[20:23]
	v_mfma_f32_16x16x32_bf16 v[20:23], v[172:175], v[192:195], v[20:23]
	v_mfma_f32_16x16x32_bf16 v[12:15], v[168:171], v[196:199], v[12:15]
	v_mfma_f32_16x16x32_bf16 v[12:15], v[172:175], v[200:203], v[12:15]
	v_mfma_f32_16x16x32_bf16 v[2:5], v[168:171], v[204:207], v[2:5]
	v_mfma_f32_16x16x32_bf16 v[8:11], v[164:167], v[208:211], v[6:9]
	v_mfma_f32_16x16x32_bf16 v[4:7], v[172:175], v[208:211], v[2:5]
	s_setprio 0
	s_barrier
	s_add_u32 s16, s16, 0x100
	s_addc_u32 s17, s17, 0
	s_add_u32 s50, s50, 0x100
	s_addc_u32 s51, s51, 0
	s_cmp_ge_u32 s52, s11
	s_mov_b32 s20, s52
	s_cbranch_scc0 .LBB0_1913
	v_readlane_b32 s14, v253, 2
	v_readlane_b32 s15, v253, 3
	s_and_b64 vcc, exec, s[14:15]
	s_cbranch_vccz .LBB0_1916
	s_barrier

.LBB0_1997:
	s_add_u32 s22, s16, 0xfff80080
	s_addc_u32 s23, s17, -1
	s_add_i32 s69, 0, 0x10000
	s_cmp_eq_u32 s25, 28
	s_cselect_b32 s27, s11, s23
	s_cselect_b32 s26, s18, s22
	s_cselect_b32 s23, s9, s24
	s_cselect_b32 s22, s19, s21
	s_add_i32 s72, 0, 0x14000
	v_add_u32_e32 v142, s69, v205
	v_add_u32_e32 v162, s72, v205
	ds_read_b128 v[130:133], v142
	ds_read_b128 v[134:137], v142 offset:1024
	ds_read_b128 v[138:141], v142 offset:2048
	ds_read_b128 v[142:145], v142 offset:3072
	ds_read_b128 v[146:149], v162
	ds_read_b128 v[150:153], v162 offset:1024
	ds_read_b128 v[154:157], v162 offset:2048
	ds_read_b128 v[162:165], v162 offset:3072
	s_add_i32 m0, s54, 0xc000
	ds_read_b128 v[166:169], v230
	ds_read_b128 v[170:173], v230 offset:1024
	ds_read_b128 v[184:187], v230 offset:2048
	ds_read_b128 v[188:191], v230 offset:3072
	ds_read_b128 v[192:195], v230 offset:4096
	ds_read_b128 v[196:199], v230 offset:5120
	ds_read_b128 v[200:203], v230 offset:6144
	ds_read_b128 v[232:235], v230 offset:7168
	global_load_lds_dwordx4 v180, s[16:17]
	s_add_i32 m0, s54, 0xe000
	s_nop 0
	global_load_lds_dwordx4 v182, s[16:17]
	s_waitcnt vmcnt(8)
	s_waitcnt lgkmcnt(0)
	s_barrier
	s_setprio 1
	s_waitcnt lgkmcnt(0)
	v_mfma_f32_16x16x32_bf16 v[126:129], v[130:133], v[166:169], v[126:129]
	v_mfma_f32_16x16x32_bf16 v[126:129], v[134:137], v[170:173], v[126:129]
	v_mfma_f32_16x16x32_bf16 v[118:121], v[130:133], v[184:187], v[118:121]
	v_mfma_f32_16x16x32_bf16 v[118:121], v[134:137], v[188:191], v[118:121]
	v_mfma_f32_16x16x32_bf16 v[110:113], v[130:133], v[192:195], v[110:113]
	v_mfma_f32_16x16x32_bf16 v[110:113], v[134:137], v[196:199], v[110:113]
	v_mfma_f32_16x16x32_bf16 v[102:105], v[130:133], v[200:203], v[102:105]
	v_mfma_f32_16x16x32_bf16 v[102:105], v[134:137], v[232:235], v[102:105]
	v_mfma_f32_16x16x32_bf16 v[74:77], v[138:141], v[166:169], v[74:77]
	v_mfma_f32_16x16x32_bf16 v[74:77], v[142:145], v[170:173], v[74:77]
	v_mfma_f32_16x16x32_bf16 v[86:89], v[138:141], v[184:187], v[86:89]
	v_mfma_f32_16x16x32_bf16 v[86:89], v[142:145], v[188:191], v[86:89]
	v_mfma_f32_16x16x32_bf16 v[66:69], v[138:141], v[192:195], v[66:69]
	v_mfma_f32_16x16x32_bf16 v[66:69], v[142:145], v[196:199], v[66:69]
	v_mfma_f32_16x16x32_bf16 v[38:41], v[138:141], v[200:203], v[38:41]
	v_mfma_f32_16x16x32_bf16 v[38:41], v[142:145], v[232:235], v[38:41]
	v_mfma_f32_16x16x32_bf16 v[122:125], v[146:149], v[166:169], v[122:125]
	v_mfma_f32_16x16x32_bf16 v[122:125], v[150:153], v[170:173], v[122:125]
	v_mfma_f32_16x16x32_bf16 v[114:117], v[146:149], v[184:187], v[114:117]
	v_mfma_f32_16x16x32_bf16 v[114:117], v[150:153], v[188:191], v[114:117]
	v_mfma_f32_16x16x32_bf16 v[106:109], v[146:149], v[192:195], v[106:109]
	v_mfma_f32_16x16x32_bf16 v[106:109], v[150:153], v[196:199], v[106:109]
	v_mfma_f32_16x16x32_bf16 v[98:101], v[146:149], v[200:203], v[98:101]
	v_mfma_f32_16x16x32_bf16 v[98:101], v[150:153], v[232:235], v[98:101]
	v_mfma_f32_16x16x32_bf16 v[82:85], v[154:157], v[166:169], v[82:85]
	v_mfma_f32_16x16x32_bf16 v[82:85], v[162:165], v[170:173], v[82:85]
	v_mfma_f32_16x16x32_bf16 v[90:93], v[154:157], v[184:187], v[90:93]
	v_mfma_f32_16x16x32_bf16 v[90:93], v[162:165], v[188:191], v[90:93]
	v_mfma_f32_16x16x32_bf16 v[70:73], v[154:157], v[192:195], v[70:73]
	v_mfma_f32_16x16x32_bf16 v[70:73], v[162:165], v[196:199], v[70:73]
	v_mfma_f32_16x16x32_bf16 v[42:45], v[154:157], v[200:203], v[42:45]
	v_mfma_f32_16x16x32_bf16 v[42:45], v[162:165], v[232:235], v[42:45]
	s_setprio 0
	s_barrier
	s_add_i32 s69, s69, s33
	v_lshl_add_u64 v[212:213], s[22:23], 0, v[0:1]
	s_mov_b32 m0, s69
	ds_read_b128 v[166:169], v230 offset:16384
	ds_read_b128 v[170:173], v230 offset:17408
	ds_read_b128 v[184:187], v230 offset:18432
	ds_read_b128 v[188:191], v230 offset:19456
	ds_read_b128 v[192:195], v230 offset:20480
	ds_read_b128 v[196:199], v230 offset:21504
	ds_read_b128 v[200:203], v230 offset:22528
	ds_read_b128 v[232:235], v230 offset:23552
	global_load_lds_dwordx4 v[212:213], off
	s_add_i32 m0, s69, 0x2000
	s_add_u32 s70, s22, 0x80000
	v_lshl_add_u64 v[220:221], s[22:23], 0, v[158:159]
	s_addc_u32 s71, s23, 0
	s_add_i32 s69, s72, s33
	global_load_lds_dwordx4 v[220:221], off
	s_mov_b32 m0, s69
	v_lshl_add_u64 v[238:239], s[26:27], 0, v[160:161]
	global_load_lds_dwordx4 v0, s[70:71]
	s_add_i32 m0, s69, 0x2000
	s_nop 0
	global_load_lds_dwordx4 v158, s[70:71]
	v_lshl_add_u64 v[236:237], s[26:27], 0, v[174:175]
	s_mov_b32 m0, s54
	s_nop 0
	global_load_lds_dwordx4 v[236:237], off
	s_mov_b32 m0, s55
	s_nop 0
	global_load_lds_dwordx4 v[238:239], off
	s_waitcnt vmcnt(8)
	s_waitcnt lgkmcnt(0)
	s_barrier
	s_setprio 1
	s_waitcnt lgkmcnt(0)
	v_mfma_f32_16x16x32_bf16 v[94:97], v[130:133], v[166:169], v[94:97]
	v_mfma_f32_16x16x32_bf16 v[94:97], v[134:137], v[170:173], v[94:97]
	v_mfma_f32_16x16x32_bf16 v[62:65], v[130:133], v[184:187], v[62:65]
	v_mfma_f32_16x16x32_bf16 v[62:65], v[134:137], v[188:191], v[62:65]
	v_mfma_f32_16x16x32_bf16 v[46:49], v[130:133], v[192:195], v[46:49]
	v_mfma_f32_16x16x32_bf16 v[46:49], v[134:137], v[196:199], v[46:49]
	v_mfma_f32_16x16x32_bf16 v[22:25], v[130:133], v[200:203], v[22:25]
	v_mfma_f32_16x16x32_bf16 v[22:25], v[134:137], v[232:235], v[22:25]
	v_mfma_f32_16x16x32_bf16 v[50:53], v[138:141], v[166:169], v[50:53]
	v_mfma_f32_16x16x32_bf16 v[50:53], v[142:145], v[170:173], v[50:53]
	v_mfma_f32_16x16x32_bf16 v[30:33], v[138:141], v[184:187], v[30:33]
	v_mfma_f32_16x16x32_bf16 v[30:33], v[142:145], v[188:191], v[30:33]
	v_mfma_f32_16x16x32_bf16 v[10:13], v[138:141], v[192:195], v[10:13]
	v_mfma_f32_16x16x32_bf16 v[10:13], v[142:145], v[196:199], v[10:13]
	v_mfma_f32_16x16x32_bf16 v[2:5], v[138:141], v[200:203], v[2:5]
	v_mfma_f32_16x16x32_bf16 v[2:5], v[142:145], v[232:235], v[2:5]
	v_mfma_f32_16x16x32_bf16 v[78:81], v[146:149], v[166:169], v[78:81]
	v_mfma_f32_16x16x32_bf16 v[78:81], v[150:153], v[170:173], v[78:81]
	v_mfma_f32_16x16x32_bf16 v[54:57], v[146:149], v[184:187], v[54:57]
	v_mfma_f32_16x16x32_bf16 v[54:57], v[150:153], v[188:191], v[54:57]
	v_mfma_f32_16x16x32_bf16 v[26:29], v[146:149], v[192:195], v[26:29]
	v_mfma_f32_16x16x32_bf16 v[26:29], v[150:153], v[196:199], v[26:29]
	v_mfma_f32_16x16x32_bf16 v[18:21], v[146:149], v[200:203], v[18:21]
	v_mfma_f32_16x16x32_bf16 v[18:21], v[150:153], v[232:235], v[18:21]
	v_mfma_f32_16x16x32_bf16 v[58:61], v[154:157], v[166:169], v[58:61]
	v_mfma_f32_16x16x32_bf16 v[58:61], v[162:165], v[170:173], v[58:61]
	v_mfma_f32_16x16x32_bf16 v[34:37], v[154:157], v[184:187], v[34:37]
	v_mfma_f32_16x16x32_bf16 v[34:37], v[162:165], v[188:191], v[34:37]
	v_mfma_f32_16x16x32_bf16 v[14:17], v[154:157], v[192:195], v[14:17]
	v_mfma_f32_16x16x32_bf16 v[14:17], v[162:165], v[196:199], v[14:17]
	v_mfma_f32_16x16x32_bf16 v[6:9], v[154:157], v[200:203], v[6:9]
	v_mfma_f32_16x16x32_bf16 v[6:9], v[162:165], v[232:235], v[6:9]
	s_setprio 0
	s_barrier
	s_add_i32 s69, 0, 0x18000
	s_add_i32 s70, 0, 0x1c000
	v_add_u32_e32 v142, s69, v205
	v_add_u32_e32 v162, s70, v205
	ds_read_b128 v[130:133], v142
	ds_read_b128 v[134:137], v142 offset:1024
	ds_read_b128 v[138:141], v142 offset:2048
	ds_read_b128 v[142:145], v142 offset:3072
	ds_read_b128 v[146:149], v162
	ds_read_b128 v[150:153], v162 offset:1024
	ds_read_b128 v[154:157], v162 offset:2048
	ds_read_b128 v[162:165], v162 offset:3072
	s_add_u32 s26, s26, 0x80000
	s_addc_u32 s27, s27, 0
	s_mov_b32 m0, s56
	ds_read_b128 v[166:169], v230 offset:32768
	ds_read_b128 v[170:173], v230 offset:33792
	ds_read_b128 v[184:187], v230 offset:34816
	ds_read_b128 v[188:191], v230 offset:35840
	ds_read_b128 v[192:195], v230 offset:36864
	ds_read_b128 v[196:199], v230 offset:37888
	ds_read_b128 v[200:203], v230 offset:38912
	ds_read_b128 v[232:235], v230 offset:39936
	global_load_lds_dwordx4 v174, s[26:27]
	s_mov_b32 m0, s57
	s_nop 0
	global_load_lds_dwordx4 v160, s[26:27]
	s_waitcnt vmcnt(8)
	s_waitcnt lgkmcnt(0)
	s_barrier
	s_setprio 1
	s_waitcnt lgkmcnt(0)
	v_mfma_f32_16x16x32_bf16 v[126:129], v[130:133], v[166:169], v[126:129]
	v_mfma_f32_16x16x32_bf16 v[126:129], v[134:137], v[170:173], v[126:129]
	v_mfma_f32_16x16x32_bf16 v[118:121], v[130:133], v[184:187], v[118:121]
	v_mfma_f32_16x16x32_bf16 v[118:121], v[134:137], v[188:191], v[118:121]
	v_mfma_f32_16x16x32_bf16 v[110:113], v[130:133], v[192:195], v[110:113]
	v_mfma_f32_16x16x32_bf16 v[110:113], v[134:137], v[196:199], v[110:113]
	v_mfma_f32_16x16x32_bf16 v[102:105], v[130:133], v[200:203], v[102:105]
	v_mfma_f32_16x16x32_bf16 v[102:105], v[134:137], v[232:235], v[102:105]
	v_mfma_f32_16x16x32_bf16 v[74:77], v[138:141], v[166:169], v[74:77]
	v_mfma_f32_16x16x32_bf16 v[74:77], v[142:145], v[170:173], v[74:77]
	v_mfma_f32_16x16x32_bf16 v[86:89], v[138:141], v[184:187], v[86:89]
	v_mfma_f32_16x16x32_bf16 v[86:89], v[142:145], v[188:191], v[86:89]
	v_mfma_f32_16x16x32_bf16 v[66:69], v[138:141], v[192:195], v[66:69]
	v_mfma_f32_16x16x32_bf16 v[66:69], v[142:145], v[196:199], v[66:69]
	v_mfma_f32_16x16x32_bf16 v[38:41], v[138:141], v[200:203], v[38:41]
	v_mfma_f32_16x16x32_bf16 v[38:41], v[142:145], v[232:235], v[38:41]
	v_mfma_f32_16x16x32_bf16 v[122:125], v[146:149], v[166:169], v[122:125]
	v_mfma_f32_16x16x32_bf16 v[122:125], v[150:153], v[170:173], v[122:125]
	v_mfma_f32_16x16x32_bf16 v[114:117], v[146:149], v[184:187], v[114:117]
	v_mfma_f32_16x16x32_bf16 v[114:117], v[150:153], v[188:191], v[114:117]
	v_mfma_f32_16x16x32_bf16 v[106:109], v[146:149], v[192:195], v[106:109]
	v_mfma_f32_16x16x32_bf16 v[106:109], v[150:153], v[196:199], v[106:109]
	v_mfma_f32_16x16x32_bf16 v[98:101], v[146:149], v[200:203], v[98:101]
	v_mfma_f32_16x16x32_bf16 v[98:101], v[150:153], v[232:235], v[98:101]
	v_mfma_f32_16x16x32_bf16 v[82:85], v[154:157], v[166:169], v[82:85]
	v_mfma_f32_16x16x32_bf16 v[82:85], v[162:165], v[170:173], v[82:85]
	v_mfma_f32_16x16x32_bf16 v[90:93], v[154:157], v[184:187], v[90:93]
	v_mfma_f32_16x16x32_bf16 v[90:93], v[162:165], v[188:191], v[90:93]
	v_mfma_f32_16x16x32_bf16 v[70:73], v[154:157], v[192:195], v[70:73]
	v_mfma_f32_16x16x32_bf16 v[70:73], v[162:165], v[196:199], v[70:73]
	v_mfma_f32_16x16x32_bf16 v[42:45], v[154:157], v[200:203], v[42:45]
	v_mfma_f32_16x16x32_bf16 v[42:45], v[162:165], v[232:235], v[42:45]
	s_setprio 0
	s_barrier
	s_add_i32 s26, s69, s33
	v_lshl_add_u64 v[212:213], v[212:213], 0, s[30:31]
	s_mov_b32 m0, s26
	ds_read_b128 v[166:169], v230 offset:49152
	ds_read_b128 v[170:173], v230 offset:50176
	ds_read_b128 v[184:187], v230 offset:51200
	ds_read_b128 v[188:191], v230 offset:52224
	ds_read_b128 v[192:195], v230 offset:53248
	ds_read_b128 v[196:199], v230 offset:54272
	ds_read_b128 v[200:203], v230 offset:55296
	ds_read_b128 v[232:235], v230 offset:56320
	global_load_lds_dwordx4 v[212:213], off
	s_add_i32 m0, s26, 0x2000
	s_add_u32 s22, s22, 0x80080
	v_lshl_add_u64 v[212:213], v[220:221], 0, s[30:31]
	s_addc_u32 s23, s23, 0
	s_add_i32 s26, s70, s33
	global_load_lds_dwordx4 v[212:213], off
	s_mov_b32 m0, s26
	s_nop 0
	global_load_lds_dwordx4 v0, s[22:23]
	s_add_i32 m0, s26, 0x2000
	s_nop 0
	global_load_lds_dwordx4 v158, s[22:23]
	v_lshl_add_u64 v[212:213], v[236:237], 0, s[30:31]
	s_mov_b32 m0, s59
	s_nop 0
	global_load_lds_dwordx4 v[212:213], off
	v_lshl_add_u64 v[212:213], v[238:239], 0, s[30:31]
	s_mov_b32 m0, s60
	s_nop 0
	global_load_lds_dwordx4 v[212:213], off
	s_waitcnt vmcnt(8)
	s_waitcnt lgkmcnt(0)
	s_barrier
	s_setprio 1
	s_waitcnt lgkmcnt(0)
	v_mfma_f32_16x16x32_bf16 v[94:97], v[130:133], v[166:169], v[94:97]
	v_mfma_f32_16x16x32_bf16 v[94:97], v[134:137], v[170:173], v[94:97]
	v_mfma_f32_16x16x32_bf16 v[62:65], v[130:133], v[184:187], v[62:65]
	v_mfma_f32_16x16x32_bf16 v[62:65], v[134:137], v[188:191], v[62:65]
	v_mfma_f32_16x16x32_bf16 v[46:49], v[130:133], v[192:195], v[46:49]
	v_mfma_f32_16x16x32_bf16 v[46:49], v[134:137], v[196:199], v[46:49]
	v_mfma_f32_16x16x32_bf16 v[22:25], v[130:133], v[200:203], v[22:25]
	v_mfma_f32_16x16x32_bf16 v[22:25], v[134:137], v[232:235], v[22:25]
	v_mfma_f32_16x16x32_bf16 v[50:53], v[138:141], v[166:169], v[50:53]
	v_mfma_f32_16x16x32_bf16 v[50:53], v[142:145], v[170:173], v[50:53]
	v_mfma_f32_16x16x32_bf16 v[30:33], v[138:141], v[184:187], v[30:33]
	v_mfma_f32_16x16x32_bf16 v[30:33], v[142:145], v[188:191], v[30:33]
	v_mfma_f32_16x16x32_bf16 v[10:13], v[138:141], v[192:195], v[10:13]
	v_mfma_f32_16x16x32_bf16 v[10:13], v[142:145], v[196:199], v[10:13]
	v_mfma_f32_16x16x32_bf16 v[2:5], v[138:141], v[200:203], v[2:5]
	v_mfma_f32_16x16x32_bf16 v[2:5], v[142:145], v[232:235], v[2:5]
	v_mfma_f32_16x16x32_bf16 v[78:81], v[146:149], v[166:169], v[78:81]
	v_mfma_f32_16x16x32_bf16 v[78:81], v[150:153], v[170:173], v[78:81]
	v_mfma_f32_16x16x32_bf16 v[54:57], v[146:149], v[184:187], v[54:57]
	v_mfma_f32_16x16x32_bf16 v[54:57], v[150:153], v[188:191], v[54:57]
	v_mfma_f32_16x16x32_bf16 v[26:29], v[146:149], v[192:195], v[26:29]
	v_mfma_f32_16x16x32_bf16 v[26:29], v[150:153], v[196:199], v[26:29]
	v_mfma_f32_16x16x32_bf16 v[18:21], v[146:149], v[200:203], v[18:21]
	v_mfma_f32_16x16x32_bf16 v[18:21], v[150:153], v[232:235], v[18:21]
	v_mfma_f32_16x16x32_bf16 v[58:61], v[154:157], v[166:169], v[58:61]
	v_mfma_f32_16x16x32_bf16 v[58:61], v[162:165], v[170:173], v[58:61]
	v_mfma_f32_16x16x32_bf16 v[34:37], v[154:157], v[184:187], v[34:37]
	v_mfma_f32_16x16x32_bf16 v[34:37], v[162:165], v[188:191], v[34:37]
	v_mfma_f32_16x16x32_bf16 v[14:17], v[154:157], v[192:195], v[14:17]
	v_mfma_f32_16x16x32_bf16 v[14:17], v[162:165], v[196:199], v[14:17]
	v_mfma_f32_16x16x32_bf16 v[6:9], v[154:157], v[200:203], v[6:9]
	v_mfma_f32_16x16x32_bf16 v[6:9], v[162:165], v[232:235], v[6:9]
	s_setprio 0
	s_barrier
	s_add_i32 s25, s25, 2
	s_add_u32 s16, s16, 0x100
	s_addc_u32 s17, s17, 0
	s_add_u32 s21, s21, 0x100
	s_addc_u32 s24, s24, 0
	s_cmp_gt_u32 s25, 29
	s_cbranch_scc0 .LBB0_1997
	v_readlane_b32 s16, v253, 2
	v_readlane_b32 s17, v253, 3
	s_and_b64 vcc, exec, s[16:17]
	s_cbranch_vccz .LBB0_2000
	s_barrier

.LBB0_2111:
	s_add_u32 s16, s14, 0xfffc0080
	s_addc_u32 s17, s15, -1
	s_add_i32 s51, 0, 0x10000
	s_cmp_eq_u32 s50, 12
	s_cselect_b32 s21, s9, s17
	s_cselect_b32 s20, s46, s16
	s_cselect_b32 s17, s5, s49
	s_cselect_b32 s16, s47, s48
	s_add_i32 s54, 0, 0x14000
	v_add_u32_e32 v154, s51, v181
	v_add_u32_e32 v170, s54, v181
	ds_read_b128 v[130:133], v154
	ds_read_b128 v[134:137], v154 offset:1024
	ds_read_b128 v[150:153], v154 offset:2048
	ds_read_b128 v[154:157], v154 offset:3072
	ds_read_b128 v[158:161], v170
	ds_read_b128 v[162:165], v170 offset:1024
	ds_read_b128 v[166:169], v170 offset:2048
	ds_read_b128 v[170:173], v170 offset:3072
	s_add_i32 m0, s26, 0xc000
	ds_read_b128 v[174:177], v184
	ds_read_b128 v[186:189], v184 offset:1024
	ds_read_b128 v[190:193], v184 offset:2048
	ds_read_b128 v[194:197], v184 offset:3072
	ds_read_b128 v[198:201], v184 offset:4096
	ds_read_b128 v[202:205], v184 offset:5120
	ds_read_b128 v[206:209], v184 offset:6144
	ds_read_b128 v[210:213], v184 offset:7168
	global_load_lds_dwordx4 v146, s[14:15]
	s_add_i32 m0, s26, 0xe000
	s_nop 0
	global_load_lds_dwordx4 v148, s[14:15]
	s_waitcnt vmcnt(8)
	s_waitcnt lgkmcnt(0)
	s_barrier
	s_setprio 1
	s_waitcnt lgkmcnt(0)
	v_mfma_i32_16x16x64_i8 v[126:129], v[130:133], v[174:177], v[126:129]
	v_mfma_i32_16x16x64_i8 v[126:129], v[134:137], v[186:189], v[126:129]
	v_mfma_i32_16x16x64_i8 v[110:113], v[130:133], v[190:193], v[110:113]
	v_mfma_i32_16x16x64_i8 v[110:113], v[134:137], v[194:197], v[110:113]
	v_mfma_i32_16x16x64_i8 v[94:97], v[130:133], v[198:201], v[94:97]
	v_mfma_i32_16x16x64_i8 v[94:97], v[134:137], v[202:205], v[94:97]
	v_mfma_i32_16x16x64_i8 v[78:81], v[130:133], v[206:209], v[78:81]
	v_mfma_i32_16x16x64_i8 v[78:81], v[134:137], v[210:213], v[78:81]
	v_mfma_i32_16x16x64_i8 v[122:125], v[150:153], v[174:177], v[122:125]
	v_mfma_i32_16x16x64_i8 v[122:125], v[154:157], v[186:189], v[122:125]
	v_mfma_i32_16x16x64_i8 v[102:105], v[150:153], v[190:193], v[102:105]
	v_mfma_i32_16x16x64_i8 v[102:105], v[154:157], v[194:197], v[102:105]
	v_mfma_i32_16x16x64_i8 v[86:89], v[150:153], v[198:201], v[86:89]
	v_mfma_i32_16x16x64_i8 v[86:89], v[154:157], v[202:205], v[86:89]
	v_mfma_i32_16x16x64_i8 v[70:73], v[150:153], v[206:209], v[70:73]
	v_mfma_i32_16x16x64_i8 v[70:73], v[154:157], v[210:213], v[70:73]
	v_mfma_i32_16x16x64_i8 v[118:121], v[158:161], v[174:177], v[118:121]
	v_mfma_i32_16x16x64_i8 v[118:121], v[162:165], v[186:189], v[118:121]
	v_mfma_i32_16x16x64_i8 v[106:109], v[158:161], v[190:193], v[106:109]
	v_mfma_i32_16x16x64_i8 v[106:109], v[162:165], v[194:197], v[106:109]
	v_mfma_i32_16x16x64_i8 v[90:93], v[158:161], v[198:201], v[90:93]
	v_mfma_i32_16x16x64_i8 v[90:93], v[162:165], v[202:205], v[90:93]
	v_mfma_i32_16x16x64_i8 v[74:77], v[158:161], v[206:209], v[74:77]
	v_mfma_i32_16x16x64_i8 v[74:77], v[162:165], v[210:213], v[74:77]
	v_mfma_i32_16x16x64_i8 v[114:117], v[166:169], v[174:177], v[114:117]
	v_mfma_i32_16x16x64_i8 v[114:117], v[170:173], v[186:189], v[114:117]
	v_mfma_i32_16x16x64_i8 v[98:101], v[166:169], v[190:193], v[98:101]
	v_mfma_i32_16x16x64_i8 v[98:101], v[170:173], v[194:197], v[98:101]
	v_mfma_i32_16x16x64_i8 v[82:85], v[166:169], v[198:201], v[82:85]
	v_mfma_i32_16x16x64_i8 v[82:85], v[170:173], v[202:205], v[82:85]
	v_mfma_i32_16x16x64_i8 v[66:69], v[166:169], v[206:209], v[66:69]
	v_mfma_i32_16x16x64_i8 v[66:69], v[170:173], v[210:213], v[66:69]
	s_setprio 0
	s_barrier
	s_add_i32 s51, s51, s33
	v_lshl_add_u64 v[178:179], s[16:17], 0, v[0:1]
	s_mov_b32 m0, s51
	ds_read_b128 v[174:177], v184 offset:16384
	ds_read_b128 v[186:189], v184 offset:17408
	ds_read_b128 v[190:193], v184 offset:18432
	ds_read_b128 v[194:197], v184 offset:19456
	ds_read_b128 v[198:201], v184 offset:20480
	ds_read_b128 v[202:205], v184 offset:21504
	ds_read_b128 v[206:209], v184 offset:22528
	ds_read_b128 v[210:213], v184 offset:23552
	global_load_lds_dwordx4 v[178:179], off
	s_add_i32 m0, s51, 0x2000
	s_add_u32 s52, s16, 0x40000
	v_lshl_add_u64 v[220:221], s[16:17], 0, v[138:139]
	s_addc_u32 s53, s17, 0
	s_add_i32 s51, s54, s33
	global_load_lds_dwordx4 v[220:221], off
	s_mov_b32 m0, s51
	v_lshl_add_u64 v[226:227], s[20:21], 0, v[140:141]
	global_load_lds_dwordx4 v0, s[52:53]
	s_add_i32 m0, s51, 0x2000
	s_nop 0
	global_load_lds_dwordx4 v138, s[52:53]
	v_lshl_add_u64 v[224:225], s[20:21], 0, v[142:143]
	s_mov_b32 m0, s26
	s_nop 0
	global_load_lds_dwordx4 v[224:225], off
	s_mov_b32 m0, s27
	s_nop 0
	global_load_lds_dwordx4 v[226:227], off
	s_waitcnt vmcnt(8)
	s_waitcnt lgkmcnt(0)
	s_barrier
	s_setprio 1
	s_waitcnt lgkmcnt(0)
	v_mfma_i32_16x16x64_i8 v[62:65], v[130:133], v[174:177], v[62:65]
	v_mfma_i32_16x16x64_i8 v[62:65], v[134:137], v[186:189], v[62:65]
	v_mfma_i32_16x16x64_i8 v[46:49], v[130:133], v[190:193], v[46:49]
	v_mfma_i32_16x16x64_i8 v[46:49], v[134:137], v[194:197], v[46:49]
	v_mfma_i32_16x16x64_i8 v[30:33], v[130:133], v[198:201], v[30:33]
	v_mfma_i32_16x16x64_i8 v[30:33], v[134:137], v[202:205], v[30:33]
	v_mfma_i32_16x16x64_i8 v[14:17], v[130:133], v[206:209], v[14:17]
	v_mfma_i32_16x16x64_i8 v[14:17], v[134:137], v[210:213], v[14:17]
	v_mfma_i32_16x16x64_i8 v[54:57], v[150:153], v[174:177], v[54:57]
	v_mfma_i32_16x16x64_i8 v[54:57], v[154:157], v[186:189], v[54:57]
	v_mfma_i32_16x16x64_i8 v[38:41], v[150:153], v[190:193], v[38:41]
	v_mfma_i32_16x16x64_i8 v[38:41], v[154:157], v[194:197], v[38:41]
	v_mfma_i32_16x16x64_i8 v[22:25], v[150:153], v[198:201], v[22:25]
	v_mfma_i32_16x16x64_i8 v[22:25], v[154:157], v[202:205], v[22:25]
	v_mfma_i32_16x16x64_i8 v[6:9], v[150:153], v[206:209], v[6:9]
	v_mfma_i32_16x16x64_i8 v[6:9], v[154:157], v[210:213], v[6:9]
	v_mfma_i32_16x16x64_i8 v[58:61], v[158:161], v[174:177], v[58:61]
	v_mfma_i32_16x16x64_i8 v[58:61], v[162:165], v[186:189], v[58:61]
	v_mfma_i32_16x16x64_i8 v[42:45], v[158:161], v[190:193], v[42:45]
	v_mfma_i32_16x16x64_i8 v[42:45], v[162:165], v[194:197], v[42:45]
	v_mfma_i32_16x16x64_i8 v[26:29], v[158:161], v[198:201], v[26:29]
	v_mfma_i32_16x16x64_i8 v[26:29], v[162:165], v[202:205], v[26:29]
	v_mfma_i32_16x16x64_i8 v[10:13], v[158:161], v[206:209], v[10:13]
	v_mfma_i32_16x16x64_i8 v[10:13], v[162:165], v[210:213], v[10:13]
	v_mfma_i32_16x16x64_i8 v[50:53], v[166:169], v[174:177], v[50:53]
	v_mfma_i32_16x16x64_i8 v[50:53], v[170:173], v[186:189], v[50:53]
	v_mfma_i32_16x16x64_i8 v[34:37], v[166:169], v[190:193], v[34:37]
	v_mfma_i32_16x16x64_i8 v[34:37], v[170:173], v[194:197], v[34:37]
	v_mfma_i32_16x16x64_i8 v[18:21], v[166:169], v[198:201], v[18:21]
	v_mfma_i32_16x16x64_i8 v[18:21], v[170:173], v[202:205], v[18:21]
	v_mfma_i32_16x16x64_i8 v[2:5], v[166:169], v[206:209], v[2:5]
	v_mfma_i32_16x16x64_i8 v[2:5], v[170:173], v[210:213], v[2:5]
	s_setprio 0
	s_barrier
	s_add_i32 s51, 0, 0x18000
	s_add_i32 s52, 0, 0x1c000
	v_add_u32_e32 v154, s51, v181
	v_add_u32_e32 v170, s52, v181
	ds_read_b128 v[130:133], v154
	ds_read_b128 v[134:137], v154 offset:1024
	ds_read_b128 v[150:153], v154 offset:2048
	ds_read_b128 v[154:157], v154 offset:3072
	ds_read_b128 v[158:161], v170
	ds_read_b128 v[162:165], v170 offset:1024
	ds_read_b128 v[166:169], v170 offset:2048
	ds_read_b128 v[170:173], v170 offset:3072
	s_add_u32 s20, s20, 0x40000
	s_addc_u32 s21, s21, 0
	s_mov_b32 m0, s28
	ds_read_b128 v[174:177], v184 offset:32768
	ds_read_b128 v[186:189], v184 offset:33792
	ds_read_b128 v[190:193], v184 offset:34816
	ds_read_b128 v[194:197], v184 offset:35840
	ds_read_b128 v[198:201], v184 offset:36864
	ds_read_b128 v[202:205], v184 offset:37888
	ds_read_b128 v[206:209], v184 offset:38912
	ds_read_b128 v[210:213], v184 offset:39936
	global_load_lds_dwordx4 v142, s[20:21]
	s_mov_b32 m0, s29
	s_nop 0
	global_load_lds_dwordx4 v140, s[20:21]
	s_waitcnt vmcnt(8)
	s_waitcnt lgkmcnt(0)
	s_barrier
	s_setprio 1
	s_waitcnt lgkmcnt(0)
	v_mfma_i32_16x16x64_i8 v[126:129], v[130:133], v[174:177], v[126:129]
	v_mfma_i32_16x16x64_i8 v[126:129], v[134:137], v[186:189], v[126:129]
	v_mfma_i32_16x16x64_i8 v[110:113], v[130:133], v[190:193], v[110:113]
	v_mfma_i32_16x16x64_i8 v[110:113], v[134:137], v[194:197], v[110:113]
	v_mfma_i32_16x16x64_i8 v[94:97], v[130:133], v[198:201], v[94:97]
	v_mfma_i32_16x16x64_i8 v[94:97], v[134:137], v[202:205], v[94:97]
	v_mfma_i32_16x16x64_i8 v[78:81], v[130:133], v[206:209], v[78:81]
	v_mfma_i32_16x16x64_i8 v[78:81], v[134:137], v[210:213], v[78:81]
	v_mfma_i32_16x16x64_i8 v[122:125], v[150:153], v[174:177], v[122:125]
	v_mfma_i32_16x16x64_i8 v[122:125], v[154:157], v[186:189], v[122:125]
	v_mfma_i32_16x16x64_i8 v[102:105], v[150:153], v[190:193], v[102:105]
	v_mfma_i32_16x16x64_i8 v[102:105], v[154:157], v[194:197], v[102:105]
	v_mfma_i32_16x16x64_i8 v[86:89], v[150:153], v[198:201], v[86:89]
	v_mfma_i32_16x16x64_i8 v[86:89], v[154:157], v[202:205], v[86:89]
	v_mfma_i32_16x16x64_i8 v[70:73], v[150:153], v[206:209], v[70:73]
	v_mfma_i32_16x16x64_i8 v[70:73], v[154:157], v[210:213], v[70:73]
	v_mfma_i32_16x16x64_i8 v[118:121], v[158:161], v[174:177], v[118:121]
	v_mfma_i32_16x16x64_i8 v[118:121], v[162:165], v[186:189], v[118:121]
	v_mfma_i32_16x16x64_i8 v[106:109], v[158:161], v[190:193], v[106:109]
	v_mfma_i32_16x16x64_i8 v[106:109], v[162:165], v[194:197], v[106:109]
	v_mfma_i32_16x16x64_i8 v[90:93], v[158:161], v[198:201], v[90:93]
	v_mfma_i32_16x16x64_i8 v[90:93], v[162:165], v[202:205], v[90:93]
	v_mfma_i32_16x16x64_i8 v[74:77], v[158:161], v[206:209], v[74:77]
	v_mfma_i32_16x16x64_i8 v[74:77], v[162:165], v[210:213], v[74:77]
	v_mfma_i32_16x16x64_i8 v[114:117], v[166:169], v[174:177], v[114:117]
	v_mfma_i32_16x16x64_i8 v[114:117], v[170:173], v[186:189], v[114:117]
	v_mfma_i32_16x16x64_i8 v[98:101], v[166:169], v[190:193], v[98:101]
	v_mfma_i32_16x16x64_i8 v[98:101], v[170:173], v[194:197], v[98:101]
	v_mfma_i32_16x16x64_i8 v[82:85], v[166:169], v[198:201], v[82:85]
	v_mfma_i32_16x16x64_i8 v[82:85], v[170:173], v[202:205], v[82:85]
	v_mfma_i32_16x16x64_i8 v[66:69], v[166:169], v[206:209], v[66:69]
	v_mfma_i32_16x16x64_i8 v[66:69], v[170:173], v[210:213], v[66:69]
	s_setprio 0
	s_barrier
	s_add_i32 s20, s51, s33
	v_lshl_add_u64 v[178:179], v[178:179], 0, s[30:31]
	s_mov_b32 m0, s20
	ds_read_b128 v[174:177], v184 offset:49152
	ds_read_b128 v[186:189], v184 offset:50176
	ds_read_b128 v[190:193], v184 offset:51200
	ds_read_b128 v[194:197], v184 offset:52224
	ds_read_b128 v[198:201], v184 offset:53248
	ds_read_b128 v[202:205], v184 offset:54272
	ds_read_b128 v[206:209], v184 offset:55296
	ds_read_b128 v[210:213], v184 offset:56320
	global_load_lds_dwordx4 v[178:179], off
	s_add_i32 m0, s20, 0x2000
	s_add_u32 s16, s16, 0x40080
	v_lshl_add_u64 v[178:179], v[220:221], 0, s[30:31]
	s_addc_u32 s17, s17, 0
	s_add_i32 s20, s52, s33
	global_load_lds_dwordx4 v[178:179], off
	s_mov_b32 m0, s20
	s_nop 0
	global_load_lds_dwordx4 v0, s[16:17]
	s_add_i32 m0, s20, 0x2000
	s_nop 0
	global_load_lds_dwordx4 v138, s[16:17]
	v_lshl_add_u64 v[178:179], v[224:225], 0, s[30:31]
	s_mov_b32 m0, s34
	s_nop 0
	global_load_lds_dwordx4 v[178:179], off
	v_lshl_add_u64 v[178:179], v[226:227], 0, s[30:31]
	s_mov_b32 m0, s35
	s_nop 0
	global_load_lds_dwordx4 v[178:179], off
	s_waitcnt vmcnt(8)
	s_waitcnt lgkmcnt(0)
	s_barrier
	s_setprio 1
	s_waitcnt lgkmcnt(0)
	v_mfma_i32_16x16x64_i8 v[62:65], v[130:133], v[174:177], v[62:65]
	v_mfma_i32_16x16x64_i8 v[62:65], v[134:137], v[186:189], v[62:65]
	v_mfma_i32_16x16x64_i8 v[46:49], v[130:133], v[190:193], v[46:49]
	v_mfma_i32_16x16x64_i8 v[46:49], v[134:137], v[194:197], v[46:49]
	v_mfma_i32_16x16x64_i8 v[30:33], v[130:133], v[198:201], v[30:33]
	v_mfma_i32_16x16x64_i8 v[30:33], v[134:137], v[202:205], v[30:33]
	v_mfma_i32_16x16x64_i8 v[14:17], v[130:133], v[206:209], v[14:17]
	v_mfma_i32_16x16x64_i8 v[14:17], v[134:137], v[210:213], v[14:17]
	v_mfma_i32_16x16x64_i8 v[54:57], v[150:153], v[174:177], v[54:57]
	v_mfma_i32_16x16x64_i8 v[54:57], v[154:157], v[186:189], v[54:57]
	v_mfma_i32_16x16x64_i8 v[38:41], v[150:153], v[190:193], v[38:41]
	v_mfma_i32_16x16x64_i8 v[38:41], v[154:157], v[194:197], v[38:41]
	v_mfma_i32_16x16x64_i8 v[22:25], v[150:153], v[198:201], v[22:25]
	v_mfma_i32_16x16x64_i8 v[22:25], v[154:157], v[202:205], v[22:25]
	v_mfma_i32_16x16x64_i8 v[6:9], v[150:153], v[206:209], v[6:9]
	v_mfma_i32_16x16x64_i8 v[6:9], v[154:157], v[210:213], v[6:9]
	v_mfma_i32_16x16x64_i8 v[58:61], v[158:161], v[174:177], v[58:61]
	v_mfma_i32_16x16x64_i8 v[58:61], v[162:165], v[186:189], v[58:61]
	v_mfma_i32_16x16x64_i8 v[42:45], v[158:161], v[190:193], v[42:45]
	v_mfma_i32_16x16x64_i8 v[42:45], v[162:165], v[194:197], v[42:45]
	v_mfma_i32_16x16x64_i8 v[26:29], v[158:161], v[198:201], v[26:29]
	v_mfma_i32_16x16x64_i8 v[26:29], v[162:165], v[202:205], v[26:29]
	v_mfma_i32_16x16x64_i8 v[10:13], v[158:161], v[206:209], v[10:13]
	v_mfma_i32_16x16x64_i8 v[10:13], v[162:165], v[210:213], v[10:13]
	v_mfma_i32_16x16x64_i8 v[50:53], v[166:169], v[174:177], v[50:53]
	v_mfma_i32_16x16x64_i8 v[50:53], v[170:173], v[186:189], v[50:53]
	v_mfma_i32_16x16x64_i8 v[34:37], v[166:169], v[190:193], v[34:37]
	v_mfma_i32_16x16x64_i8 v[34:37], v[170:173], v[194:197], v[34:37]
	v_mfma_i32_16x16x64_i8 v[18:21], v[166:169], v[198:201], v[18:21]
	v_mfma_i32_16x16x64_i8 v[18:21], v[170:173], v[202:205], v[18:21]
	v_mfma_i32_16x16x64_i8 v[2:5], v[166:169], v[206:209], v[2:5]
	v_mfma_i32_16x16x64_i8 v[2:5], v[170:173], v[210:213], v[2:5]
	s_setprio 0
	s_barrier
	s_add_i32 s50, s50, 2
	s_add_u32 s14, s14, 0x100
	s_addc_u32 s15, s15, 0
	s_add_u32 s48, s48, 0x100
	s_addc_u32 s49, s49, 0
	s_cmp_gt_u32 s50, 13
	s_cbranch_scc0 .LBB0_2111
	v_readlane_b32 s14, v253, 2
	v_readlane_b32 s15, v253, 3
	s_and_b64 vcc, exec, s[14:15]
	s_cbranch_vccz .LBB0_2114
	s_barrier

.LBB0_2193:
	s_add_u32 s16, s12, 0x100
	s_addc_u32 s17, s13, 0
	s_add_i32 s67, 0, 0x10000
	s_cmpk_eq_i32 s19, 0x54
	s_cselect_b32 s23, s7, s17
	s_cselect_b32 s22, s6, s16
	s_cselect_b32 s21, s11, s18
	s_cselect_b32 s20, s10, s15
	s_add_i32 s68, 0, 0x14000
	v_add_u32_e32 v142, s67, v205
	v_add_u32_e32 v162, s68, v205
	ds_read_b128 v[130:133], v142
	ds_read_b128 v[134:137], v142 offset:1024
	ds_read_b128 v[138:141], v142 offset:2048
	ds_read_b128 v[142:145], v142 offset:3072
	ds_read_b128 v[146:149], v162
	ds_read_b128 v[150:153], v162 offset:1024
	ds_read_b128 v[154:157], v162 offset:2048
	ds_read_b128 v[162:165], v162 offset:3072
	s_add_i32 m0, s28, 0xc000
	ds_read_b128 v[166:169], v230
	ds_read_b128 v[170:173], v230 offset:1024
	ds_read_b128 v[184:187], v230 offset:2048
	ds_read_b128 v[188:191], v230 offset:3072
	ds_read_b128 v[192:195], v230 offset:4096
	ds_read_b128 v[196:199], v230 offset:5120
	ds_read_b128 v[200:203], v230 offset:6144
	ds_read_b128 v[232:235], v230 offset:7168
	global_load_lds_dwordx4 v180, s[12:13]
	s_add_i32 m0, s28, 0xe000
	s_nop 0
	global_load_lds_dwordx4 v182, s[12:13]
	s_waitcnt vmcnt(8)
	s_waitcnt lgkmcnt(0)
	s_barrier
	s_setprio 1
	s_waitcnt lgkmcnt(0)
	v_mfma_f32_16x16x32_bf16 v[126:129], v[130:133], v[166:169], v[126:129]
	v_mfma_f32_16x16x32_bf16 v[126:129], v[134:137], v[170:173], v[126:129]
	v_mfma_f32_16x16x32_bf16 v[118:121], v[130:133], v[184:187], v[118:121]
	v_mfma_f32_16x16x32_bf16 v[118:121], v[134:137], v[188:191], v[118:121]
	v_mfma_f32_16x16x32_bf16 v[110:113], v[130:133], v[192:195], v[110:113]
	v_mfma_f32_16x16x32_bf16 v[110:113], v[134:137], v[196:199], v[110:113]
	v_mfma_f32_16x16x32_bf16 v[102:105], v[130:133], v[200:203], v[102:105]
	v_mfma_f32_16x16x32_bf16 v[102:105], v[134:137], v[232:235], v[102:105]
	v_mfma_f32_16x16x32_bf16 v[74:77], v[138:141], v[166:169], v[74:77]
	v_mfma_f32_16x16x32_bf16 v[74:77], v[142:145], v[170:173], v[74:77]
	v_mfma_f32_16x16x32_bf16 v[86:89], v[138:141], v[184:187], v[86:89]
	v_mfma_f32_16x16x32_bf16 v[86:89], v[142:145], v[188:191], v[86:89]
	v_mfma_f32_16x16x32_bf16 v[66:69], v[138:141], v[192:195], v[66:69]
	v_mfma_f32_16x16x32_bf16 v[66:69], v[142:145], v[196:199], v[66:69]
	v_mfma_f32_16x16x32_bf16 v[38:41], v[138:141], v[200:203], v[38:41]
	v_mfma_f32_16x16x32_bf16 v[38:41], v[142:145], v[232:235], v[38:41]
	v_mfma_f32_16x16x32_bf16 v[122:125], v[146:149], v[166:169], v[122:125]
	v_mfma_f32_16x16x32_bf16 v[122:125], v[150:153], v[170:173], v[122:125]
	v_mfma_f32_16x16x32_bf16 v[114:117], v[146:149], v[184:187], v[114:117]
	v_mfma_f32_16x16x32_bf16 v[114:117], v[150:153], v[188:191], v[114:117]
	v_mfma_f32_16x16x32_bf16 v[106:109], v[146:149], v[192:195], v[106:109]
	v_mfma_f32_16x16x32_bf16 v[106:109], v[150:153], v[196:199], v[106:109]
	v_mfma_f32_16x16x32_bf16 v[98:101], v[146:149], v[200:203], v[98:101]
	v_mfma_f32_16x16x32_bf16 v[98:101], v[150:153], v[232:235], v[98:101]
	v_mfma_f32_16x16x32_bf16 v[82:85], v[154:157], v[166:169], v[82:85]
	v_mfma_f32_16x16x32_bf16 v[82:85], v[162:165], v[170:173], v[82:85]
	v_mfma_f32_16x16x32_bf16 v[90:93], v[154:157], v[184:187], v[90:93]
	v_mfma_f32_16x16x32_bf16 v[90:93], v[162:165], v[188:191], v[90:93]
	v_mfma_f32_16x16x32_bf16 v[70:73], v[154:157], v[192:195], v[70:73]
	v_mfma_f32_16x16x32_bf16 v[70:73], v[162:165], v[196:199], v[70:73]
	v_mfma_f32_16x16x32_bf16 v[42:45], v[154:157], v[200:203], v[42:45]
	v_mfma_f32_16x16x32_bf16 v[42:45], v[162:165], v[232:235], v[42:45]
	s_setprio 0
	s_barrier
	s_add_i32 s12, s67, s33
	v_lshl_add_u64 v[212:213], s[20:21], 0, v[0:1]
	s_mov_b32 m0, s12
	ds_read_b128 v[166:169], v230 offset:16384
	ds_read_b128 v[170:173], v230 offset:17408
	ds_read_b128 v[184:187], v230 offset:18432
	ds_read_b128 v[188:191], v230 offset:19456
	ds_read_b128 v[192:195], v230 offset:20480
	ds_read_b128 v[196:199], v230 offset:21504
	ds_read_b128 v[200:203], v230 offset:22528
	ds_read_b128 v[232:235], v230 offset:23552
	global_load_lds_dwordx4 v[212:213], off
	s_add_i32 m0, s12, 0x2000
	s_add_u32 s12, s20, 0x160000
	v_lshl_add_u64 v[220:221], s[20:21], 0, v[158:159]
	s_addc_u32 s13, s21, 0
	s_add_i32 s67, s68, s33
	global_load_lds_dwordx4 v[220:221], off
	s_mov_b32 m0, s67
	v_lshl_add_u64 v[238:239], s[22:23], 0, v[160:161]
	global_load_lds_dwordx4 v0, s[12:13]
	s_add_i32 m0, s67, 0x2000
	s_nop 0
	global_load_lds_dwordx4 v158, s[12:13]
	v_lshl_add_u64 v[236:237], s[22:23], 0, v[174:175]
	s_mov_b32 m0, s28
	s_nop 0
	global_load_lds_dwordx4 v[236:237], off
	s_mov_b32 m0, s29
	s_nop 0
	global_load_lds_dwordx4 v[238:239], off
	s_waitcnt vmcnt(8)
	s_waitcnt lgkmcnt(0)
	s_barrier
	s_setprio 1
	s_waitcnt lgkmcnt(0)
	v_mfma_f32_16x16x32_bf16 v[94:97], v[130:133], v[166:169], v[94:97]
	v_mfma_f32_16x16x32_bf16 v[94:97], v[134:137], v[170:173], v[94:97]
	v_mfma_f32_16x16x32_bf16 v[62:65], v[130:133], v[184:187], v[62:65]
	v_mfma_f32_16x16x32_bf16 v[62:65], v[134:137], v[188:191], v[62:65]
	v_mfma_f32_16x16x32_bf16 v[46:49], v[130:133], v[192:195], v[46:49]
	v_mfma_f32_16x16x32_bf16 v[46:49], v[134:137], v[196:199], v[46:49]
	v_mfma_f32_16x16x32_bf16 v[22:25], v[130:133], v[200:203], v[22:25]
	v_mfma_f32_16x16x32_bf16 v[22:25], v[134:137], v[232:235], v[22:25]
	v_mfma_f32_16x16x32_bf16 v[50:53], v[138:141], v[166:169], v[50:53]
	v_mfma_f32_16x16x32_bf16 v[50:53], v[142:145], v[170:173], v[50:53]
	v_mfma_f32_16x16x32_bf16 v[30:33], v[138:141], v[184:187], v[30:33]
	v_mfma_f32_16x16x32_bf16 v[30:33], v[142:145], v[188:191], v[30:33]
	v_mfma_f32_16x16x32_bf16 v[10:13], v[138:141], v[192:195], v[10:13]
	v_mfma_f32_16x16x32_bf16 v[10:13], v[142:145], v[196:199], v[10:13]
	v_mfma_f32_16x16x32_bf16 v[2:5], v[138:141], v[200:203], v[2:5]
	v_mfma_f32_16x16x32_bf16 v[2:5], v[142:145], v[232:235], v[2:5]
	v_mfma_f32_16x16x32_bf16 v[78:81], v[146:149], v[166:169], v[78:81]
	v_mfma_f32_16x16x32_bf16 v[78:81], v[150:153], v[170:173], v[78:81]
	v_mfma_f32_16x16x32_bf16 v[54:57], v[146:149], v[184:187], v[54:57]
	v_mfma_f32_16x16x32_bf16 v[54:57], v[150:153], v[188:191], v[54:57]
	v_mfma_f32_16x16x32_bf16 v[26:29], v[146:149], v[192:195], v[26:29]
	v_mfma_f32_16x16x32_bf16 v[26:29], v[150:153], v[196:199], v[26:29]
	v_mfma_f32_16x16x32_bf16 v[18:21], v[146:149], v[200:203], v[18:21]
	v_mfma_f32_16x16x32_bf16 v[18:21], v[150:153], v[232:235], v[18:21]
	v_mfma_f32_16x16x32_bf16 v[58:61], v[154:157], v[166:169], v[58:61]
	v_mfma_f32_16x16x32_bf16 v[58:61], v[162:165], v[170:173], v[58:61]
	v_mfma_f32_16x16x32_bf16 v[34:37], v[154:157], v[184:187], v[34:37]
	v_mfma_f32_16x16x32_bf16 v[34:37], v[162:165], v[188:191], v[34:37]
	v_mfma_f32_16x16x32_bf16 v[14:17], v[154:157], v[192:195], v[14:17]
	v_mfma_f32_16x16x32_bf16 v[14:17], v[162:165], v[196:199], v[14:17]
	v_mfma_f32_16x16x32_bf16 v[6:9], v[154:157], v[200:203], v[6:9]
	v_mfma_f32_16x16x32_bf16 v[6:9], v[162:165], v[232:235], v[6:9]
	s_setprio 0
	s_barrier
	s_add_i32 s67, 0, 0x18000
	s_add_i32 s68, 0, 0x1c000
	v_add_u32_e32 v142, s67, v205
	v_add_u32_e32 v162, s68, v205
	ds_read_b128 v[130:133], v142
	ds_read_b128 v[134:137], v142 offset:1024
	ds_read_b128 v[138:141], v142 offset:2048
	ds_read_b128 v[142:145], v142 offset:3072
	ds_read_b128 v[146:149], v162
	ds_read_b128 v[150:153], v162 offset:1024
	ds_read_b128 v[154:157], v162 offset:2048
	ds_read_b128 v[162:165], v162 offset:3072
	s_add_u32 s12, s22, 0x160000
	s_addc_u32 s13, s23, 0
	s_mov_b32 m0, s34
	ds_read_b128 v[166:169], v230 offset:32768
	ds_read_b128 v[170:173], v230 offset:33792
	ds_read_b128 v[184:187], v230 offset:34816
	ds_read_b128 v[188:191], v230 offset:35840
	ds_read_b128 v[192:195], v230 offset:36864
	ds_read_b128 v[196:199], v230 offset:37888
	ds_read_b128 v[200:203], v230 offset:38912
	ds_read_b128 v[232:235], v230 offset:39936
	global_load_lds_dwordx4 v174, s[12:13]
	s_mov_b32 m0, s35
	s_nop 0
	global_load_lds_dwordx4 v160, s[12:13]
	s_waitcnt vmcnt(8)
	s_waitcnt lgkmcnt(0)
	s_barrier
	s_setprio 1
	s_waitcnt lgkmcnt(0)
	v_mfma_f32_16x16x32_bf16 v[126:129], v[130:133], v[166:169], v[126:129]
	v_mfma_f32_16x16x32_bf16 v[126:129], v[134:137], v[170:173], v[126:129]
	v_mfma_f32_16x16x32_bf16 v[118:121], v[130:133], v[184:187], v[118:121]
	v_mfma_f32_16x16x32_bf16 v[118:121], v[134:137], v[188:191], v[118:121]
	v_mfma_f32_16x16x32_bf16 v[110:113], v[130:133], v[192:195], v[110:113]
	v_mfma_f32_16x16x32_bf16 v[110:113], v[134:137], v[196:199], v[110:113]
	v_mfma_f32_16x16x32_bf16 v[102:105], v[130:133], v[200:203], v[102:105]
	v_mfma_f32_16x16x32_bf16 v[102:105], v[134:137], v[232:235], v[102:105]
	v_mfma_f32_16x16x32_bf16 v[74:77], v[138:141], v[166:169], v[74:77]
	v_mfma_f32_16x16x32_bf16 v[74:77], v[142:145], v[170:173], v[74:77]
	v_mfma_f32_16x16x32_bf16 v[86:89], v[138:141], v[184:187], v[86:89]
	v_mfma_f32_16x16x32_bf16 v[86:89], v[142:145], v[188:191], v[86:89]
	v_mfma_f32_16x16x32_bf16 v[66:69], v[138:141], v[192:195], v[66:69]
	v_mfma_f32_16x16x32_bf16 v[66:69], v[142:145], v[196:199], v[66:69]
	v_mfma_f32_16x16x32_bf16 v[38:41], v[138:141], v[200:203], v[38:41]
	v_mfma_f32_16x16x32_bf16 v[38:41], v[142:145], v[232:235], v[38:41]
	v_mfma_f32_16x16x32_bf16 v[122:125], v[146:149], v[166:169], v[122:125]
	v_mfma_f32_16x16x32_bf16 v[122:125], v[150:153], v[170:173], v[122:125]
	v_mfma_f32_16x16x32_bf16 v[114:117], v[146:149], v[184:187], v[114:117]
	v_mfma_f32_16x16x32_bf16 v[114:117], v[150:153], v[188:191], v[114:117]
	v_mfma_f32_16x16x32_bf16 v[106:109], v[146:149], v[192:195], v[106:109]
	v_mfma_f32_16x16x32_bf16 v[106:109], v[150:153], v[196:199], v[106:109]
	v_mfma_f32_16x16x32_bf16 v[98:101], v[146:149], v[200:203], v[98:101]
	v_mfma_f32_16x16x32_bf16 v[98:101], v[150:153], v[232:235], v[98:101]
	v_mfma_f32_16x16x32_bf16 v[82:85], v[154:157], v[166:169], v[82:85]
	v_mfma_f32_16x16x32_bf16 v[82:85], v[162:165], v[170:173], v[82:85]
	v_mfma_f32_16x16x32_bf16 v[90:93], v[154:157], v[184:187], v[90:93]
	v_mfma_f32_16x16x32_bf16 v[90:93], v[162:165], v[188:191], v[90:93]
	v_mfma_f32_16x16x32_bf16 v[70:73], v[154:157], v[192:195], v[70:73]
	v_mfma_f32_16x16x32_bf16 v[70:73], v[162:165], v[196:199], v[70:73]
	v_mfma_f32_16x16x32_bf16 v[42:45], v[154:157], v[200:203], v[42:45]
	v_mfma_f32_16x16x32_bf16 v[42:45], v[162:165], v[232:235], v[42:45]
	s_setprio 0
	s_barrier
	s_add_i32 s12, s67, s33
	v_lshl_add_u64 v[212:213], v[212:213], 0, s[30:31]
	s_mov_b32 m0, s12
	ds_read_b128 v[166:169], v230 offset:49152
	ds_read_b128 v[170:173], v230 offset:50176
	ds_read_b128 v[184:187], v230 offset:51200
	ds_read_b128 v[188:191], v230 offset:52224
	ds_read_b128 v[192:195], v230 offset:53248
	ds_read_b128 v[196:199], v230 offset:54272
	ds_read_b128 v[200:203], v230 offset:55296
	ds_read_b128 v[232:235], v230 offset:56320
	global_load_lds_dwordx4 v[212:213], off
	s_add_i32 m0, s12, 0x2000
	s_add_u32 s12, s20, 0x160080
	v_lshl_add_u64 v[212:213], v[220:221], 0, s[30:31]
	s_addc_u32 s13, s21, 0
	s_add_i32 s20, s68, s33
	global_load_lds_dwordx4 v[212:213], off
	s_mov_b32 m0, s20
	s_nop 0
	global_load_lds_dwordx4 v0, s[12:13]
	s_add_i32 m0, s20, 0x2000
	s_nop 0
	global_load_lds_dwordx4 v158, s[12:13]
	v_lshl_add_u64 v[212:213], v[236:237], 0, s[30:31]
	s_mov_b32 m0, s55
	s_nop 0
	global_load_lds_dwordx4 v[212:213], off
	v_lshl_add_u64 v[212:213], v[238:239], 0, s[30:31]
	s_mov_b32 m0, s56
	s_nop 0
	global_load_lds_dwordx4 v[212:213], off
	s_waitcnt vmcnt(8)
	s_waitcnt lgkmcnt(0)
	s_barrier
	s_setprio 1
	s_waitcnt lgkmcnt(0)
	v_mfma_f32_16x16x32_bf16 v[94:97], v[130:133], v[166:169], v[94:97]
	v_mfma_f32_16x16x32_bf16 v[94:97], v[134:137], v[170:173], v[94:97]
	v_mfma_f32_16x16x32_bf16 v[62:65], v[130:133], v[184:187], v[62:65]
	v_mfma_f32_16x16x32_bf16 v[62:65], v[134:137], v[188:191], v[62:65]
	v_mfma_f32_16x16x32_bf16 v[46:49], v[130:133], v[192:195], v[46:49]
	v_mfma_f32_16x16x32_bf16 v[46:49], v[134:137], v[196:199], v[46:49]
	v_mfma_f32_16x16x32_bf16 v[22:25], v[130:133], v[200:203], v[22:25]
	v_mfma_f32_16x16x32_bf16 v[22:25], v[134:137], v[232:235], v[22:25]
	v_mfma_f32_16x16x32_bf16 v[50:53], v[138:141], v[166:169], v[50:53]
	v_mfma_f32_16x16x32_bf16 v[50:53], v[142:145], v[170:173], v[50:53]
	v_mfma_f32_16x16x32_bf16 v[30:33], v[138:141], v[184:187], v[30:33]
	v_mfma_f32_16x16x32_bf16 v[30:33], v[142:145], v[188:191], v[30:33]
	v_mfma_f32_16x16x32_bf16 v[10:13], v[138:141], v[192:195], v[10:13]
	v_mfma_f32_16x16x32_bf16 v[10:13], v[142:145], v[196:199], v[10:13]
	v_mfma_f32_16x16x32_bf16 v[2:5], v[138:141], v[200:203], v[2:5]
	v_mfma_f32_16x16x32_bf16 v[2:5], v[142:145], v[232:235], v[2:5]
	v_mfma_f32_16x16x32_bf16 v[78:81], v[146:149], v[166:169], v[78:81]
	v_mfma_f32_16x16x32_bf16 v[78:81], v[150:153], v[170:173], v[78:81]
	v_mfma_f32_16x16x32_bf16 v[54:57], v[146:149], v[184:187], v[54:57]
	v_mfma_f32_16x16x32_bf16 v[54:57], v[150:153], v[188:191], v[54:57]
	v_mfma_f32_16x16x32_bf16 v[26:29], v[146:149], v[192:195], v[26:29]
	v_mfma_f32_16x16x32_bf16 v[26:29], v[150:153], v[196:199], v[26:29]
	v_mfma_f32_16x16x32_bf16 v[18:21], v[146:149], v[200:203], v[18:21]
	v_mfma_f32_16x16x32_bf16 v[18:21], v[150:153], v[232:235], v[18:21]
	v_mfma_f32_16x16x32_bf16 v[58:61], v[154:157], v[166:169], v[58:61]
	v_mfma_f32_16x16x32_bf16 v[58:61], v[162:165], v[170:173], v[58:61]
	v_mfma_f32_16x16x32_bf16 v[34:37], v[154:157], v[184:187], v[34:37]
	v_mfma_f32_16x16x32_bf16 v[34:37], v[162:165], v[188:191], v[34:37]
	v_mfma_f32_16x16x32_bf16 v[14:17], v[154:157], v[192:195], v[14:17]
	v_mfma_f32_16x16x32_bf16 v[14:17], v[162:165], v[196:199], v[14:17]
	v_mfma_f32_16x16x32_bf16 v[6:9], v[154:157], v[200:203], v[6:9]
	v_mfma_f32_16x16x32_bf16 v[6:9], v[162:165], v[232:235], v[6:9]
	s_setprio 0
	s_barrier
	s_add_i32 s19, s19, 2
	s_add_u32 s15, s15, 0x100
	s_addc_u32 s18, s18, 0
	s_cmpk_gt_u32 s19, 0x55
	s_mov_b64 s[12:13], s[16:17]
	s_cbranch_scc0 .LBB0_2193
	v_readlane_b32 s12, v253, 2
	v_readlane_b32 s13, v253, 3
	s_and_b64 vcc, exec, s[12:13]
	s_cbranch_vccz .LBB0_2196
	s_barrier
